# s_setprio 1 raised during the MFMA phase of every pipelined GEMM k-tile (lowered for fragment reads and barrier)
# speedup vs baseline: 1.0701x; 1.0402x over previous
.Lgm_p1_loop:
	ds_read_b128 v[178:181], v115 offset:16384
	ds_read_b128 v[156:159], v114
	ds_read_b128 v[182:185], v115 offset:18432
	ds_read_b128 v[186:189], v115 offset:20480
	ds_read_b128 v[190:193], v115 offset:22528
	ds_read_b128 v[166:169], v114 offset:2048
	ds_read_b128 v[170:173], v114 offset:4096
	ds_read_b128 v[174:177], v114 offset:6144
	ds_read_b128 v[194:197], v117 offset:16384
	ds_read_b128 v[198:201], v117 offset:18432
	ds_read_b128 v[202:205], v117 offset:20480
	ds_read_b128 v[206:209], v117 offset:22528
	s_setprio 1
	s_waitcnt lgkmcnt(7)
	v_mfma_f32_16x16x32_bf16 v[92:95], v[178:181], v[156:159], v[92:95]
	v_mfma_f32_16x16x32_bf16 v[88:91], v[182:185], v[156:159], v[88:91]
	v_mfma_f32_16x16x32_bf16 v[84:87], v[186:189], v[156:159], v[84:87]
	v_mfma_f32_16x16x32_bf16 v[0:3], v[190:193], v[156:159], v[0:3]
	ds_read_b128 v[156:159], v116
	s_waitcnt lgkmcnt(5)
	v_mfma_f32_16x16x32_bf16 v[28:31], v[178:181], v[166:169], v[28:31]
	s_waitcnt vmcnt(8)
	ds_write_b128 v103, v[118:121] offset:32768
	v_mfma_f32_16x16x32_bf16 v[72:75], v[182:185], v[166:169], v[72:75]
	ds_write_b128 v103, v[140:143] offset:49152
	v_mfma_f32_16x16x32_bf16 v[68:71], v[186:189], v[166:169], v[68:71]
	ds_write_b128 v103, v[122:125] offset:36864
	v_mfma_f32_16x16x32_bf16 v[4:7], v[190:193], v[166:169], v[4:7]
	ds_read_b128 v[166:169], v116 offset:2048
	v_mfma_f32_16x16x32_bf16 v[32:35], v[178:181], v[170:173], v[32:35]
	ds_write_b128 v103, v[144:147] offset:53248
	v_mfma_f32_16x16x32_bf16 v[56:59], v[182:185], v[170:173], v[56:59]
	ds_write_b128 v103, v[126:129] offset:40960
	v_mfma_f32_16x16x32_bf16 v[52:55], v[186:189], v[170:173], v[52:55]
	ds_write_b128 v103, v[148:151] offset:57344
	v_mfma_f32_16x16x32_bf16 v[8:11], v[190:193], v[170:173], v[8:11]
	ds_read_b128 v[170:173], v116 offset:4096
	v_mfma_f32_16x16x32_bf16 v[16:19], v[178:181], v[174:177], v[16:19]
	ds_write_b128 v103, v[130:133] offset:45056
	v_mfma_f32_16x16x32_bf16 v[20:23], v[182:185], v[174:177], v[20:23]
	ds_write_b128 v103, v[152:155] offset:61440
	v_mfma_f32_16x16x32_bf16 v[24:27], v[186:189], v[174:177], v[24:27]
	v_mfma_f32_16x16x32_bf16 v[12:15], v[190:193], v[174:177], v[12:15]
	s_waitcnt lgkmcnt(8)
	ds_read_b128 v[174:177], v116 offset:6144
	v_mfma_f32_16x16x32_bf16 v[92:95], v[194:197], v[156:159], v[92:95]
	v_mfma_f32_16x16x32_bf16 v[88:91], v[198:201], v[156:159], v[88:91]
	v_mfma_f32_16x16x32_bf16 v[84:87], v[202:205], v[156:159], v[84:87]
	v_mfma_f32_16x16x32_bf16 v[0:3], v[206:209], v[156:159], v[0:3]
	s_waitcnt lgkmcnt(0)
	v_mfma_f32_16x16x32_bf16 v[28:31], v[194:197], v[166:169], v[28:31]
	global_load_dwordx4 v[118:121], v108, s[100:101] offset:384
	v_mfma_f32_16x16x32_bf16 v[72:75], v[198:201], v[166:169], v[72:75]
	global_load_dwordx4 v[140:143], v110, s[98:99] offset:384
	v_mfma_f32_16x16x32_bf16 v[68:71], v[202:205], v[166:169], v[68:71]
	global_load_dwordx4 v[122:125], v109, s[100:101] offset:384
	v_mfma_f32_16x16x32_bf16 v[4:7], v[206:209], v[166:169], v[4:7]
	global_load_dwordx4 v[144:147], v111, s[98:99] offset:384
	v_mfma_f32_16x16x32_bf16 v[32:35], v[194:197], v[170:173], v[32:35]
	global_load_dwordx4 v[126:129], v163, s[100:101] offset:384
	v_mfma_f32_16x16x32_bf16 v[56:59], v[198:201], v[170:173], v[56:59]
	global_load_dwordx4 v[148:151], v210, s[98:99] offset:384
	v_mfma_f32_16x16x32_bf16 v[52:55], v[202:205], v[170:173], v[52:55]
	global_load_dwordx4 v[130:133], v165, s[100:101] offset:384
	v_mfma_f32_16x16x32_bf16 v[8:11], v[206:209], v[170:173], v[8:11]
	global_load_dwordx4 v[152:155], v211, s[98:99] offset:384
	v_mfma_f32_16x16x32_bf16 v[16:19], v[194:197], v[174:177], v[16:19]
	v_mfma_f32_16x16x32_bf16 v[20:23], v[198:201], v[174:177], v[20:23]
	v_mfma_f32_16x16x32_bf16 v[24:27], v[202:205], v[174:177], v[24:27]
	v_mfma_f32_16x16x32_bf16 v[12:15], v[206:209], v[174:177], v[12:15]
	s_setprio 0
	s_barrier
	ds_read_b128 v[178:181], v115 offset:49152
	ds_read_b128 v[156:159], v114 offset:32768
	ds_read_b128 v[182:185], v115 offset:51200
	ds_read_b128 v[186:189], v115 offset:53248
	ds_read_b128 v[190:193], v115 offset:55296
	ds_read_b128 v[166:169], v114 offset:34816
	ds_read_b128 v[170:173], v114 offset:36864
	ds_read_b128 v[174:177], v114 offset:38912
	ds_read_b128 v[194:197], v117 offset:49152
	ds_read_b128 v[198:201], v117 offset:51200
	ds_read_b128 v[202:205], v117 offset:53248
	ds_read_b128 v[206:209], v117 offset:55296
	s_setprio 1
	s_waitcnt lgkmcnt(7)
	v_mfma_f32_16x16x32_bf16 v[92:95], v[178:181], v[156:159], v[92:95]
	v_mfma_f32_16x16x32_bf16 v[88:91], v[182:185], v[156:159], v[88:91]
	v_mfma_f32_16x16x32_bf16 v[84:87], v[186:189], v[156:159], v[84:87]
	v_mfma_f32_16x16x32_bf16 v[0:3], v[190:193], v[156:159], v[0:3]
	ds_read_b128 v[156:159], v116 offset:32768
	s_waitcnt lgkmcnt(5)
	v_mfma_f32_16x16x32_bf16 v[28:31], v[178:181], v[166:169], v[28:31]
	s_waitcnt vmcnt(8)
	ds_write_b128 v103, v[36:39]
	v_mfma_f32_16x16x32_bf16 v[72:75], v[182:185], v[166:169], v[72:75]
	ds_write_b128 v103, v[60:63] offset:16384
	v_mfma_f32_16x16x32_bf16 v[68:71], v[186:189], v[166:169], v[68:71]
	ds_write_b128 v103, v[40:43] offset:4096
	v_mfma_f32_16x16x32_bf16 v[4:7], v[190:193], v[166:169], v[4:7]
	ds_read_b128 v[166:169], v116 offset:34816
	v_mfma_f32_16x16x32_bf16 v[32:35], v[178:181], v[170:173], v[32:35]
	ds_write_b128 v103, v[64:67] offset:20480
	v_mfma_f32_16x16x32_bf16 v[56:59], v[182:185], v[170:173], v[56:59]
	ds_write_b128 v103, v[44:47] offset:8192
	v_mfma_f32_16x16x32_bf16 v[52:55], v[186:189], v[170:173], v[52:55]
	ds_write_b128 v103, v[76:79] offset:24576
	v_mfma_f32_16x16x32_bf16 v[8:11], v[190:193], v[170:173], v[8:11]
	ds_read_b128 v[170:173], v116 offset:36864
	v_mfma_f32_16x16x32_bf16 v[16:19], v[178:181], v[174:177], v[16:19]
	ds_write_b128 v103, v[48:51] offset:12288
	v_mfma_f32_16x16x32_bf16 v[20:23], v[182:185], v[174:177], v[20:23]
	ds_write_b128 v103, v[80:83] offset:28672
	v_mfma_f32_16x16x32_bf16 v[24:27], v[186:189], v[174:177], v[24:27]
	v_mfma_f32_16x16x32_bf16 v[12:15], v[190:193], v[174:177], v[12:15]
	s_waitcnt lgkmcnt(8)
	ds_read_b128 v[174:177], v116 offset:38912
	v_mfma_f32_16x16x32_bf16 v[92:95], v[194:197], v[156:159], v[92:95]
	v_mfma_f32_16x16x32_bf16 v[88:91], v[198:201], v[156:159], v[88:91]
	v_mfma_f32_16x16x32_bf16 v[84:87], v[202:205], v[156:159], v[84:87]
	v_mfma_f32_16x16x32_bf16 v[0:3], v[206:209], v[156:159], v[0:3]
	s_waitcnt lgkmcnt(0)
	v_mfma_f32_16x16x32_bf16 v[28:31], v[194:197], v[166:169], v[28:31]
	global_load_dwordx4 v[36:39], v108, s[100:101] offset:512
	v_mfma_f32_16x16x32_bf16 v[72:75], v[198:201], v[166:169], v[72:75]
	global_load_dwordx4 v[60:63], v110, s[98:99] offset:512
	v_mfma_f32_16x16x32_bf16 v[68:71], v[202:205], v[166:169], v[68:71]
	global_load_dwordx4 v[40:43], v109, s[100:101] offset:512
	v_mfma_f32_16x16x32_bf16 v[4:7], v[206:209], v[166:169], v[4:7]
	global_load_dwordx4 v[64:67], v111, s[98:99] offset:512
	v_mfma_f32_16x16x32_bf16 v[32:35], v[194:197], v[170:173], v[32:35]
	global_load_dwordx4 v[44:47], v163, s[100:101] offset:512
	v_mfma_f32_16x16x32_bf16 v[56:59], v[198:201], v[170:173], v[56:59]
	global_load_dwordx4 v[76:79], v210, s[98:99] offset:512
	v_mfma_f32_16x16x32_bf16 v[52:55], v[202:205], v[170:173], v[52:55]
	global_load_dwordx4 v[48:51], v165, s[100:101] offset:512
	v_mfma_f32_16x16x32_bf16 v[8:11], v[206:209], v[170:173], v[8:11]
	global_load_dwordx4 v[80:83], v211, s[98:99] offset:512
	v_mfma_f32_16x16x32_bf16 v[16:19], v[194:197], v[174:177], v[16:19]
	v_mfma_f32_16x16x32_bf16 v[20:23], v[198:201], v[174:177], v[20:23]
	v_mfma_f32_16x16x32_bf16 v[24:27], v[202:205], v[174:177], v[24:27]
	v_mfma_f32_16x16x32_bf16 v[12:15], v[206:209], v[174:177], v[12:15]
	s_setprio 0
	s_barrier
	s_add_u32 s100, s100, 0x100
	s_addc_u32 s101, s101, 0
	s_add_u32 s98, s98, 0x100
	s_addc_u32 s99, s99, 0
	s_sub_u32 s94, s94, 1
	s_cmp_lg_u32 s94, 0
	s_cbranch_scc1 .Lgm_p1_loop
	ds_read_b128 v[178:181], v115 offset:16384
	ds_read_b128 v[156:159], v114
	ds_read_b128 v[182:185], v115 offset:18432
	ds_read_b128 v[186:189], v115 offset:20480
	ds_read_b128 v[190:193], v115 offset:22528
	ds_read_b128 v[166:169], v114 offset:2048
	ds_read_b128 v[170:173], v114 offset:4096
	ds_read_b128 v[174:177], v114 offset:6144
	ds_read_b128 v[194:197], v117 offset:16384
	ds_read_b128 v[198:201], v117 offset:18432
	ds_read_b128 v[202:205], v117 offset:20480
	ds_read_b128 v[206:209], v117 offset:22528
	s_setprio 1
	s_waitcnt lgkmcnt(7)
	v_mfma_f32_16x16x32_bf16 v[92:95], v[178:181], v[156:159], v[92:95]
	v_mfma_f32_16x16x32_bf16 v[88:91], v[182:185], v[156:159], v[88:91]
	v_mfma_f32_16x16x32_bf16 v[84:87], v[186:189], v[156:159], v[84:87]
	v_mfma_f32_16x16x32_bf16 v[0:3], v[190:193], v[156:159], v[0:3]
	ds_read_b128 v[156:159], v116
	s_waitcnt lgkmcnt(5)
	v_mfma_f32_16x16x32_bf16 v[28:31], v[178:181], v[166:169], v[28:31]
	s_waitcnt vmcnt(8)
	ds_write_b128 v103, v[118:121] offset:32768
	v_mfma_f32_16x16x32_bf16 v[72:75], v[182:185], v[166:169], v[72:75]
	ds_write_b128 v103, v[140:143] offset:49152
	v_mfma_f32_16x16x32_bf16 v[68:71], v[186:189], v[166:169], v[68:71]
	ds_write_b128 v103, v[122:125] offset:36864
	v_mfma_f32_16x16x32_bf16 v[4:7], v[190:193], v[166:169], v[4:7]
	ds_read_b128 v[166:169], v116 offset:2048
	v_mfma_f32_16x16x32_bf16 v[32:35], v[178:181], v[170:173], v[32:35]
	ds_write_b128 v103, v[144:147] offset:53248
	v_mfma_f32_16x16x32_bf16 v[56:59], v[182:185], v[170:173], v[56:59]
	ds_write_b128 v103, v[126:129] offset:40960
	v_mfma_f32_16x16x32_bf16 v[52:55], v[186:189], v[170:173], v[52:55]
	ds_write_b128 v103, v[148:151] offset:57344
	v_mfma_f32_16x16x32_bf16 v[8:11], v[190:193], v[170:173], v[8:11]
	ds_read_b128 v[170:173], v116 offset:4096
	v_mfma_f32_16x16x32_bf16 v[16:19], v[178:181], v[174:177], v[16:19]
	ds_write_b128 v103, v[130:133] offset:45056
	v_mfma_f32_16x16x32_bf16 v[20:23], v[182:185], v[174:177], v[20:23]
	ds_write_b128 v103, v[152:155] offset:61440
	v_mfma_f32_16x16x32_bf16 v[24:27], v[186:189], v[174:177], v[24:27]
	v_mfma_f32_16x16x32_bf16 v[12:15], v[190:193], v[174:177], v[12:15]
	s_waitcnt lgkmcnt(8)
	ds_read_b128 v[174:177], v116 offset:6144
	v_mfma_f32_16x16x32_bf16 v[92:95], v[194:197], v[156:159], v[92:95]
	v_mfma_f32_16x16x32_bf16 v[88:91], v[198:201], v[156:159], v[88:91]
	v_mfma_f32_16x16x32_bf16 v[84:87], v[202:205], v[156:159], v[84:87]
	v_mfma_f32_16x16x32_bf16 v[0:3], v[206:209], v[156:159], v[0:3]
	s_waitcnt lgkmcnt(0)
	v_mfma_f32_16x16x32_bf16 v[28:31], v[194:197], v[166:169], v[28:31]
	global_load_dwordx4 v[118:121], v108, s[100:101] offset:384
	v_mfma_f32_16x16x32_bf16 v[72:75], v[198:201], v[166:169], v[72:75]
	global_load_dwordx4 v[140:143], v110, s[98:99] offset:384
	v_mfma_f32_16x16x32_bf16 v[68:71], v[202:205], v[166:169], v[68:71]
	global_load_dwordx4 v[122:125], v109, s[100:101] offset:384
	v_mfma_f32_16x16x32_bf16 v[4:7], v[206:209], v[166:169], v[4:7]
	global_load_dwordx4 v[144:147], v111, s[98:99] offset:384
	v_mfma_f32_16x16x32_bf16 v[32:35], v[194:197], v[170:173], v[32:35]
	global_load_dwordx4 v[126:129], v163, s[100:101] offset:384
	v_mfma_f32_16x16x32_bf16 v[56:59], v[198:201], v[170:173], v[56:59]
	global_load_dwordx4 v[148:151], v210, s[98:99] offset:384
	v_mfma_f32_16x16x32_bf16 v[52:55], v[202:205], v[170:173], v[52:55]
	global_load_dwordx4 v[130:133], v165, s[100:101] offset:384
	v_mfma_f32_16x16x32_bf16 v[8:11], v[206:209], v[170:173], v[8:11]
	global_load_dwordx4 v[152:155], v211, s[98:99] offset:384
	v_mfma_f32_16x16x32_bf16 v[16:19], v[194:197], v[174:177], v[16:19]
	v_mfma_f32_16x16x32_bf16 v[20:23], v[198:201], v[174:177], v[20:23]
	v_mfma_f32_16x16x32_bf16 v[24:27], v[202:205], v[174:177], v[24:27]
	v_mfma_f32_16x16x32_bf16 v[12:15], v[206:209], v[174:177], v[12:15]
	s_setprio 0
	s_barrier
	ds_read_b128 v[178:181], v115 offset:49152
	ds_read_b128 v[156:159], v114 offset:32768
	ds_read_b128 v[182:185], v115 offset:51200
	ds_read_b128 v[186:189], v115 offset:53248
	ds_read_b128 v[190:193], v115 offset:55296
	ds_read_b128 v[166:169], v114 offset:34816
	ds_read_b128 v[170:173], v114 offset:36864
	ds_read_b128 v[174:177], v114 offset:38912
	ds_read_b128 v[194:197], v117 offset:49152
	ds_read_b128 v[198:201], v117 offset:51200
	ds_read_b128 v[202:205], v117 offset:53248
	ds_read_b128 v[206:209], v117 offset:55296
	s_setprio 1
	s_waitcnt lgkmcnt(7)
	v_mfma_f32_16x16x32_bf16 v[92:95], v[178:181], v[156:159], v[92:95]
	v_mfma_f32_16x16x32_bf16 v[88:91], v[182:185], v[156:159], v[88:91]
	v_mfma_f32_16x16x32_bf16 v[84:87], v[186:189], v[156:159], v[84:87]
	v_mfma_f32_16x16x32_bf16 v[0:3], v[190:193], v[156:159], v[0:3]
	ds_read_b128 v[156:159], v116 offset:32768
	s_waitcnt lgkmcnt(5)
	v_mfma_f32_16x16x32_bf16 v[28:31], v[178:181], v[166:169], v[28:31]
	s_waitcnt vmcnt(8)
	ds_write_b128 v103, v[36:39]
	v_mfma_f32_16x16x32_bf16 v[72:75], v[182:185], v[166:169], v[72:75]
	ds_write_b128 v103, v[60:63] offset:16384
	v_mfma_f32_16x16x32_bf16 v[68:71], v[186:189], v[166:169], v[68:71]
	ds_write_b128 v103, v[40:43] offset:4096
	v_mfma_f32_16x16x32_bf16 v[4:7], v[190:193], v[166:169], v[4:7]
	ds_read_b128 v[166:169], v116 offset:34816
	v_mfma_f32_16x16x32_bf16 v[32:35], v[178:181], v[170:173], v[32:35]
	ds_write_b128 v103, v[64:67] offset:20480
	v_mfma_f32_16x16x32_bf16 v[56:59], v[182:185], v[170:173], v[56:59]
	ds_write_b128 v103, v[44:47] offset:8192
	v_mfma_f32_16x16x32_bf16 v[52:55], v[186:189], v[170:173], v[52:55]
	ds_write_b128 v103, v[76:79] offset:24576
	v_mfma_f32_16x16x32_bf16 v[8:11], v[190:193], v[170:173], v[8:11]
	ds_read_b128 v[170:173], v116 offset:36864
	v_mfma_f32_16x16x32_bf16 v[16:19], v[178:181], v[174:177], v[16:19]
	ds_write_b128 v103, v[48:51] offset:12288
	v_mfma_f32_16x16x32_bf16 v[20:23], v[182:185], v[174:177], v[20:23]
	ds_write_b128 v103, v[80:83] offset:28672
	v_mfma_f32_16x16x32_bf16 v[24:27], v[186:189], v[174:177], v[24:27]
	v_mfma_f32_16x16x32_bf16 v[12:15], v[190:193], v[174:177], v[12:15]
	s_waitcnt lgkmcnt(8)
	ds_read_b128 v[174:177], v116 offset:38912
	v_mfma_f32_16x16x32_bf16 v[92:95], v[194:197], v[156:159], v[92:95]
	v_mfma_f32_16x16x32_bf16 v[88:91], v[198:201], v[156:159], v[88:91]
	v_mfma_f32_16x16x32_bf16 v[84:87], v[202:205], v[156:159], v[84:87]
	v_mfma_f32_16x16x32_bf16 v[0:3], v[206:209], v[156:159], v[0:3]
	s_waitcnt lgkmcnt(0)
	v_mfma_f32_16x16x32_bf16 v[28:31], v[194:197], v[166:169], v[28:31]
	v_mfma_f32_16x16x32_bf16 v[72:75], v[198:201], v[166:169], v[72:75]
	v_mfma_f32_16x16x32_bf16 v[68:71], v[202:205], v[166:169], v[68:71]
	v_mfma_f32_16x16x32_bf16 v[4:7], v[206:209], v[166:169], v[4:7]
	v_mfma_f32_16x16x32_bf16 v[32:35], v[194:197], v[170:173], v[32:35]
	v_mfma_f32_16x16x32_bf16 v[56:59], v[198:201], v[170:173], v[56:59]
	v_mfma_f32_16x16x32_bf16 v[52:55], v[202:205], v[170:173], v[52:55]
	v_mfma_f32_16x16x32_bf16 v[8:11], v[206:209], v[170:173], v[8:11]
	v_mfma_f32_16x16x32_bf16 v[16:19], v[194:197], v[174:177], v[16:19]
	v_mfma_f32_16x16x32_bf16 v[20:23], v[198:201], v[174:177], v[20:23]
	v_mfma_f32_16x16x32_bf16 v[24:27], v[202:205], v[174:177], v[24:27]
	v_mfma_f32_16x16x32_bf16 v[12:15], v[206:209], v[174:177], v[12:15]
	s_setprio 0
	s_barrier
	ds_read_b128 v[178:181], v115 offset:16384
	ds_read_b128 v[156:159], v114
	ds_read_b128 v[182:185], v115 offset:18432
	ds_read_b128 v[186:189], v115 offset:20480
	ds_read_b128 v[190:193], v115 offset:22528
	ds_read_b128 v[166:169], v114 offset:2048
	ds_read_b128 v[170:173], v114 offset:4096
	ds_read_b128 v[174:177], v114 offset:6144
	ds_read_b128 v[194:197], v117 offset:16384
	ds_read_b128 v[198:201], v117 offset:18432
	ds_read_b128 v[202:205], v117 offset:20480
	ds_read_b128 v[206:209], v117 offset:22528
	s_setprio 1
	s_waitcnt lgkmcnt(7)
	v_mfma_f32_16x16x32_bf16 v[92:95], v[178:181], v[156:159], v[92:95]
	v_mfma_f32_16x16x32_bf16 v[88:91], v[182:185], v[156:159], v[88:91]
	v_mfma_f32_16x16x32_bf16 v[84:87], v[186:189], v[156:159], v[84:87]
	v_mfma_f32_16x16x32_bf16 v[0:3], v[190:193], v[156:159], v[0:3]
	ds_read_b128 v[156:159], v116
	s_waitcnt lgkmcnt(5)
	v_mfma_f32_16x16x32_bf16 v[28:31], v[178:181], v[166:169], v[28:31]
	s_waitcnt vmcnt(0)
	ds_write_b128 v103, v[118:121] offset:32768
	v_mfma_f32_16x16x32_bf16 v[72:75], v[182:185], v[166:169], v[72:75]
	ds_write_b128 v103, v[140:143] offset:49152
	v_mfma_f32_16x16x32_bf16 v[68:71], v[186:189], v[166:169], v[68:71]
	ds_write_b128 v103, v[122:125] offset:36864
	v_mfma_f32_16x16x32_bf16 v[4:7], v[190:193], v[166:169], v[4:7]
	ds_read_b128 v[166:169], v116 offset:2048
	v_mfma_f32_16x16x32_bf16 v[32:35], v[178:181], v[170:173], v[32:35]
	ds_write_b128 v103, v[144:147] offset:53248
	v_mfma_f32_16x16x32_bf16 v[56:59], v[182:185], v[170:173], v[56:59]
	ds_write_b128 v103, v[126:129] offset:40960
	v_mfma_f32_16x16x32_bf16 v[52:55], v[186:189], v[170:173], v[52:55]
	ds_write_b128 v103, v[148:151] offset:57344
	v_mfma_f32_16x16x32_bf16 v[8:11], v[190:193], v[170:173], v[8:11]
	ds_read_b128 v[170:173], v116 offset:4096
	v_mfma_f32_16x16x32_bf16 v[16:19], v[178:181], v[174:177], v[16:19]
	ds_write_b128 v103, v[130:133] offset:45056
	v_mfma_f32_16x16x32_bf16 v[20:23], v[182:185], v[174:177], v[20:23]
	ds_write_b128 v103, v[152:155] offset:61440
	v_mfma_f32_16x16x32_bf16 v[24:27], v[186:189], v[174:177], v[24:27]
	v_mfma_f32_16x16x32_bf16 v[12:15], v[190:193], v[174:177], v[12:15]
	s_waitcnt lgkmcnt(8)
	ds_read_b128 v[174:177], v116 offset:6144
	v_mfma_f32_16x16x32_bf16 v[92:95], v[194:197], v[156:159], v[92:95]
	v_mfma_f32_16x16x32_bf16 v[88:91], v[198:201], v[156:159], v[88:91]
	v_mfma_f32_16x16x32_bf16 v[84:87], v[202:205], v[156:159], v[84:87]
	v_mfma_f32_16x16x32_bf16 v[0:3], v[206:209], v[156:159], v[0:3]
	s_waitcnt lgkmcnt(0)
	v_mfma_f32_16x16x32_bf16 v[28:31], v[194:197], v[166:169], v[28:31]
	v_mfma_f32_16x16x32_bf16 v[72:75], v[198:201], v[166:169], v[72:75]
	v_mfma_f32_16x16x32_bf16 v[68:71], v[202:205], v[166:169], v[68:71]
	v_mfma_f32_16x16x32_bf16 v[4:7], v[206:209], v[166:169], v[4:7]
	v_mfma_f32_16x16x32_bf16 v[32:35], v[194:197], v[170:173], v[32:35]
	v_mfma_f32_16x16x32_bf16 v[56:59], v[198:201], v[170:173], v[56:59]
	v_mfma_f32_16x16x32_bf16 v[52:55], v[202:205], v[170:173], v[52:55]
	v_mfma_f32_16x16x32_bf16 v[8:11], v[206:209], v[170:173], v[8:11]
	v_mfma_f32_16x16x32_bf16 v[16:19], v[194:197], v[174:177], v[16:19]
	v_mfma_f32_16x16x32_bf16 v[20:23], v[198:201], v[174:177], v[20:23]
	v_mfma_f32_16x16x32_bf16 v[24:27], v[202:205], v[174:177], v[24:27]
	v_mfma_f32_16x16x32_bf16 v[12:15], v[206:209], v[174:177], v[12:15]
	s_setprio 0
	s_barrier
	ds_read_b128 v[178:181], v115 offset:49152
	ds_read_b128 v[156:159], v114 offset:32768
	ds_read_b128 v[182:185], v115 offset:51200
	ds_read_b128 v[186:189], v115 offset:53248
	ds_read_b128 v[190:193], v115 offset:55296
	ds_read_b128 v[166:169], v114 offset:34816
	ds_read_b128 v[170:173], v114 offset:36864
	ds_read_b128 v[174:177], v114 offset:38912
	ds_read_b128 v[194:197], v117 offset:49152
	ds_read_b128 v[198:201], v117 offset:51200
	ds_read_b128 v[202:205], v117 offset:53248
	ds_read_b128 v[206:209], v117 offset:55296
	s_setprio 1
	s_waitcnt lgkmcnt(7)
	v_mfma_f32_16x16x32_bf16 v[92:95], v[178:181], v[156:159], v[92:95]
	v_mfma_f32_16x16x32_bf16 v[88:91], v[182:185], v[156:159], v[88:91]
	v_mfma_f32_16x16x32_bf16 v[84:87], v[186:189], v[156:159], v[84:87]
	v_mfma_f32_16x16x32_bf16 v[0:3], v[190:193], v[156:159], v[0:3]
	ds_read_b128 v[156:159], v116 offset:32768
	s_waitcnt lgkmcnt(5)
	v_mfma_f32_16x16x32_bf16 v[28:31], v[178:181], v[166:169], v[28:31]
	v_mfma_f32_16x16x32_bf16 v[72:75], v[182:185], v[166:169], v[72:75]
	v_mfma_f32_16x16x32_bf16 v[68:71], v[186:189], v[166:169], v[68:71]
	v_mfma_f32_16x16x32_bf16 v[4:7], v[190:193], v[166:169], v[4:7]
	ds_read_b128 v[166:169], v116 offset:34816
	v_mfma_f32_16x16x32_bf16 v[32:35], v[178:181], v[170:173], v[32:35]
	v_mfma_f32_16x16x32_bf16 v[56:59], v[182:185], v[170:173], v[56:59]
	v_mfma_f32_16x16x32_bf16 v[52:55], v[186:189], v[170:173], v[52:55]
	v_mfma_f32_16x16x32_bf16 v[8:11], v[190:193], v[170:173], v[8:11]
	ds_read_b128 v[170:173], v116 offset:36864
	v_mfma_f32_16x16x32_bf16 v[16:19], v[178:181], v[174:177], v[16:19]
	v_mfma_f32_16x16x32_bf16 v[20:23], v[182:185], v[174:177], v[20:23]
	v_mfma_f32_16x16x32_bf16 v[24:27], v[186:189], v[174:177], v[24:27]
	v_mfma_f32_16x16x32_bf16 v[12:15], v[190:193], v[174:177], v[12:15]
	ds_read_b128 v[174:177], v116 offset:38912
	s_waitcnt lgkmcnt(3)
	v_mfma_f32_16x16x32_bf16 v[92:95], v[194:197], v[156:159], v[92:95]
	v_mfma_f32_16x16x32_bf16 v[88:91], v[198:201], v[156:159], v[88:91]
	v_mfma_f32_16x16x32_bf16 v[84:87], v[202:205], v[156:159], v[84:87]
	v_mfma_f32_16x16x32_bf16 v[0:3], v[206:209], v[156:159], v[0:3]
	s_waitcnt lgkmcnt(0)
	v_mfma_f32_16x16x32_bf16 v[28:31], v[194:197], v[166:169], v[28:31]
	v_mfma_f32_16x16x32_bf16 v[72:75], v[198:201], v[166:169], v[72:75]
	v_mfma_f32_16x16x32_bf16 v[68:71], v[202:205], v[166:169], v[68:71]
	v_mfma_f32_16x16x32_bf16 v[4:7], v[206:209], v[166:169], v[4:7]
	v_mfma_f32_16x16x32_bf16 v[32:35], v[194:197], v[170:173], v[32:35]
	v_mfma_f32_16x16x32_bf16 v[56:59], v[198:201], v[170:173], v[56:59]
	v_mfma_f32_16x16x32_bf16 v[52:55], v[202:205], v[170:173], v[52:55]
	v_mfma_f32_16x16x32_bf16 v[8:11], v[206:209], v[170:173], v[8:11]
	v_mfma_f32_16x16x32_bf16 v[16:19], v[194:197], v[174:177], v[16:19]
	v_mfma_f32_16x16x32_bf16 v[20:23], v[198:201], v[174:177], v[20:23]
	v_mfma_f32_16x16x32_bf16 v[24:27], v[202:205], v[174:177], v[24:27]
	v_mfma_f32_16x16x32_bf16 v[12:15], v[206:209], v[174:177], v[12:15]
	s_setprio 0
	s_nop 7
	v_add_u32_e32 v42, s4, v99
	v_or_b32_e32 v36, s5, v113
	v_mul_i32_i24_e32 v38, 0x1400, v42
	v_ashrrev_i32_e32 v39, 31, v38
	v_ashrrev_i32_e32 v37, 31, v36
	v_lshl_add_u64 v[38:39], s[28:29], 0, v[38:39]
	v_lshlrev_b64 v[36:37], 1, v[36:37]
	v_lshl_add_u64 v[38:39], v[38:39], 0, v[36:37]
	v_cvt_pk_bf16_f32 v0, v0, v1
	v_cvt_pk_bf16_f32 v1, v2, v3
	global_store_dwordx2 v[38:39], v[0:1], off offset:96
	v_add_u32_e32 v0, 16, v42
	v_cvt_pk_bf16_f32 v40, v92, v93
	v_cvt_pk_bf16_f32 v41, v94, v95
	v_mul_hi_i32_i24_e32 v1, 0x1400, v0
	v_mul_i32_i24_e32 v0, 0x1400, v0
	global_store_dwordx2 v[38:39], v[40:41], off
	v_cvt_pk_bf16_f32 v40, v88, v89
	v_cvt_pk_bf16_f32 v41, v90, v91
	v_lshl_add_u64 v[0:1], s[28:29], 0, v[0:1]
	global_store_dwordx2 v[38:39], v[40:41], off offset:32
	v_cvt_pk_bf16_f32 v40, v84, v85
	v_cvt_pk_bf16_f32 v41, v86, v87
	v_cvt_pk_bf16_f32 v2, v28, v29
	v_cvt_pk_bf16_f32 v3, v30, v31
	v_lshl_add_u64 v[0:1], v[0:1], 0, v[36:37]
	global_store_dwordx2 v[38:39], v[40:41], off offset:64
	global_store_dwordx2 v[0:1], v[2:3], off
	v_cvt_pk_bf16_f32 v2, v72, v73
	v_cvt_pk_bf16_f32 v3, v74, v75
	global_store_dwordx2 v[0:1], v[2:3], off offset:32
	v_cvt_pk_bf16_f32 v2, v68, v69
	v_cvt_pk_bf16_f32 v3, v70, v71
	global_store_dwordx2 v[0:1], v[2:3], off offset:64
	v_cvt_pk_bf16_f32 v2, v4, v5
	v_cvt_pk_bf16_f32 v3, v6, v7
	global_store_dwordx2 v[0:1], v[2:3], off offset:96
	v_add_u32_e32 v0, 32, v42
	v_mul_hi_i32_i24_e32 v1, 0x1400, v0
	v_mul_i32_i24_e32 v0, 0x1400, v0
	v_lshl_add_u64 v[0:1], s[28:29], 0, v[0:1]
	v_cvt_pk_bf16_f32 v2, v32, v33
	v_cvt_pk_bf16_f32 v3, v34, v35
	v_lshl_add_u64 v[0:1], v[0:1], 0, v[36:37]
	global_store_dwordx2 v[0:1], v[2:3], off
	v_cvt_pk_bf16_f32 v2, v56, v57
	v_cvt_pk_bf16_f32 v3, v58, v59
	global_store_dwordx2 v[0:1], v[2:3], off offset:32
	v_cvt_pk_bf16_f32 v2, v52, v53
	v_cvt_pk_bf16_f32 v3, v54, v55
	global_store_dwordx2 v[0:1], v[2:3], off offset:64
	v_cvt_pk_bf16_f32 v2, v8, v9
	v_cvt_pk_bf16_f32 v3, v10, v11
	global_store_dwordx2 v[0:1], v[2:3], off offset:96
	v_add_u32_e32 v0, 48, v42
	v_mul_hi_i32_i24_e32 v1, 0x1400, v0
	v_mul_i32_i24_e32 v0, 0x1400, v0
	v_lshl_add_u64 v[0:1], s[28:29], 0, v[0:1]
	v_cvt_pk_bf16_f32 v2, v16, v17
	v_cvt_pk_bf16_f32 v3, v18, v19
	v_lshl_add_u64 v[0:1], v[0:1], 0, v[36:37]
	global_store_dwordx2 v[0:1], v[2:3], off
	v_cvt_pk_bf16_f32 v2, v20, v21
	v_cvt_pk_bf16_f32 v3, v22, v23
	global_store_dwordx2 v[0:1], v[2:3], off offset:32
	v_cvt_pk_bf16_f32 v2, v24, v25
	v_cvt_pk_bf16_f32 v3, v26, v27
	global_store_dwordx2 v[0:1], v[2:3], off offset:64
	v_cvt_pk_bf16_f32 v2, v12, v13
	v_cvt_pk_bf16_f32 v3, v14, v15
	s_add_i32 s3, s3, 1
	s_mov_b64 s[0:1], 0
	global_store_dwordx2 v[0:1], v[2:3], off offset:96
	s_branch .LBB0_127

.Lgm_p5_loop:
	ds_read_b128 v[188:191], v132 offset:16384
	ds_read_b128 v[172:175], v133
	ds_read_b128 v[192:195], v132 offset:18432
	ds_read_b128 v[196:199], v132 offset:20480
	ds_read_b128 v[200:203], v132 offset:22528
	ds_read_b128 v[176:179], v133 offset:2048
	ds_read_b128 v[180:183], v133 offset:4096
	ds_read_b128 v[184:187], v133 offset:6144
	ds_read_b128 v[204:207], v130 offset:16384
	ds_read_b128 v[208:211], v130 offset:18432
	ds_read_b128 v[212:215], v130 offset:20480
	ds_read_b128 v[220:223], v130 offset:22528
	s_setprio 1
	s_waitcnt lgkmcnt(7)
	v_mfma_f32_16x16x32_bf16 v[92:95], v[188:191], v[172:175], v[92:95]
	v_mfma_f32_16x16x32_bf16 v[88:91], v[192:195], v[172:175], v[88:91]
	v_mfma_f32_16x16x32_bf16 v[84:87], v[196:199], v[172:175], v[84:87]
	v_mfma_f32_16x16x32_bf16 v[150:153], v[200:203], v[172:175], v[150:153]
	ds_read_b128 v[172:175], v131
	s_waitcnt lgkmcnt(5)
	v_mfma_f32_16x16x32_bf16 v[44:47], v[188:191], v[176:179], v[44:47]
	s_waitcnt vmcnt(8)
	ds_write_b128 v166, v[80:83] offset:32768
	v_mfma_f32_16x16x32_bf16 v[40:43], v[192:195], v[176:179], v[40:43]
	ds_write_b128 v166, v[138:141] offset:49152
	v_mfma_f32_16x16x32_bf16 v[36:39], v[196:199], v[176:179], v[36:39]
	ds_write_b128 v166, v[120:123] offset:36864
	v_mfma_f32_16x16x32_bf16 v[32:35], v[200:203], v[176:179], v[32:35]
	ds_read_b128 v[176:179], v131 offset:2048
	v_mfma_f32_16x16x32_bf16 v[28:31], v[188:191], v[180:183], v[28:31]
	ds_write_b128 v166, v[142:145] offset:53248
	v_mfma_f32_16x16x32_bf16 v[24:27], v[192:195], v[180:183], v[24:27]
	ds_write_b128 v166, v[124:127] offset:40960
	v_mfma_f32_16x16x32_bf16 v[20:23], v[196:199], v[180:183], v[20:23]
	ds_write_b128 v166, v[146:149] offset:57344
	v_mfma_f32_16x16x32_bf16 v[16:19], v[200:203], v[180:183], v[16:19]
	ds_read_b128 v[180:183], v131 offset:4096
	v_mfma_f32_16x16x32_bf16 v[12:15], v[188:191], v[184:187], v[12:15]
	ds_write_b128 v166, v[134:137] offset:45056
	v_mfma_f32_16x16x32_bf16 v[8:11], v[192:195], v[184:187], v[8:11]
	ds_write_b128 v166, v[168:171] offset:61440
	v_mfma_f32_16x16x32_bf16 v[4:7], v[196:199], v[184:187], v[4:7]
	v_mfma_f32_16x16x32_bf16 v[0:3], v[200:203], v[184:187], v[0:3]
	s_waitcnt lgkmcnt(8)
	ds_read_b128 v[184:187], v131 offset:6144
	v_mfma_f32_16x16x32_bf16 v[92:95], v[204:207], v[172:175], v[92:95]
	v_mfma_f32_16x16x32_bf16 v[88:91], v[208:211], v[172:175], v[88:91]
	v_mfma_f32_16x16x32_bf16 v[84:87], v[212:215], v[172:175], v[84:87]
	v_mfma_f32_16x16x32_bf16 v[150:153], v[220:223], v[172:175], v[150:153]
	s_waitcnt lgkmcnt(0)
	v_mfma_f32_16x16x32_bf16 v[44:47], v[204:207], v[176:179], v[44:47]
	global_load_dwordx4 v[80:83], v116, s[100:101] offset:384
	v_mfma_f32_16x16x32_bf16 v[40:43], v[208:211], v[176:179], v[40:43]
	global_load_dwordx4 v[138:141], v118, s[98:99] offset:384
	v_mfma_f32_16x16x32_bf16 v[36:39], v[212:215], v[176:179], v[36:39]
	global_load_dwordx4 v[120:123], v117, s[100:101] offset:384
	v_mfma_f32_16x16x32_bf16 v[32:35], v[220:223], v[176:179], v[32:35]
	global_load_dwordx4 v[142:145], v119, s[98:99] offset:384
	v_mfma_f32_16x16x32_bf16 v[28:31], v[204:207], v[180:183], v[28:31]
	global_load_dwordx4 v[124:127], v97, s[100:101] offset:384
	v_mfma_f32_16x16x32_bf16 v[24:27], v[208:211], v[180:183], v[24:27]
	global_load_dwordx4 v[146:149], v103, s[98:99] offset:384
	v_mfma_f32_16x16x32_bf16 v[20:23], v[212:215], v[180:183], v[20:23]
	global_load_dwordx4 v[134:137], v101, s[100:101] offset:384
	v_mfma_f32_16x16x32_bf16 v[16:19], v[220:223], v[180:183], v[16:19]
	global_load_dwordx4 v[168:171], v105, s[98:99] offset:384
	v_mfma_f32_16x16x32_bf16 v[12:15], v[204:207], v[184:187], v[12:15]
	v_mfma_f32_16x16x32_bf16 v[8:11], v[208:211], v[184:187], v[8:11]
	v_mfma_f32_16x16x32_bf16 v[4:7], v[212:215], v[184:187], v[4:7]
	v_mfma_f32_16x16x32_bf16 v[0:3], v[220:223], v[184:187], v[0:3]
	s_setprio 0
	s_barrier
	ds_read_b128 v[188:191], v132 offset:49152
	ds_read_b128 v[172:175], v133 offset:32768
	ds_read_b128 v[192:195], v132 offset:51200
	ds_read_b128 v[196:199], v132 offset:53248
	ds_read_b128 v[200:203], v132 offset:55296
	ds_read_b128 v[176:179], v133 offset:34816
	ds_read_b128 v[180:183], v133 offset:36864
	ds_read_b128 v[184:187], v133 offset:38912
	ds_read_b128 v[204:207], v130 offset:49152
	ds_read_b128 v[208:211], v130 offset:51200
	ds_read_b128 v[212:215], v130 offset:53248
	ds_read_b128 v[220:223], v130 offset:55296
	s_setprio 1
	s_waitcnt lgkmcnt(7)
	v_mfma_f32_16x16x32_bf16 v[92:95], v[188:191], v[172:175], v[92:95]
	v_mfma_f32_16x16x32_bf16 v[88:91], v[192:195], v[172:175], v[88:91]
	v_mfma_f32_16x16x32_bf16 v[84:87], v[196:199], v[172:175], v[84:87]
	v_mfma_f32_16x16x32_bf16 v[150:153], v[200:203], v[172:175], v[150:153]
	ds_read_b128 v[172:175], v131 offset:32768
	s_waitcnt lgkmcnt(5)
	v_mfma_f32_16x16x32_bf16 v[44:47], v[188:191], v[176:179], v[44:47]
	s_waitcnt vmcnt(8)
	ds_write_b128 v166, v[48:51]
	v_mfma_f32_16x16x32_bf16 v[40:43], v[192:195], v[176:179], v[40:43]
	ds_write_b128 v166, v[64:67] offset:16384
	v_mfma_f32_16x16x32_bf16 v[36:39], v[196:199], v[176:179], v[36:39]
	ds_write_b128 v166, v[52:55] offset:4096
	v_mfma_f32_16x16x32_bf16 v[32:35], v[200:203], v[176:179], v[32:35]
	ds_read_b128 v[176:179], v131 offset:34816
	v_mfma_f32_16x16x32_bf16 v[28:31], v[188:191], v[180:183], v[28:31]
	ds_write_b128 v166, v[68:71] offset:20480
	v_mfma_f32_16x16x32_bf16 v[24:27], v[192:195], v[180:183], v[24:27]
	ds_write_b128 v166, v[56:59] offset:8192
	v_mfma_f32_16x16x32_bf16 v[20:23], v[196:199], v[180:183], v[20:23]
	ds_write_b128 v166, v[72:75] offset:24576
	v_mfma_f32_16x16x32_bf16 v[16:19], v[200:203], v[180:183], v[16:19]
	ds_read_b128 v[180:183], v131 offset:36864
	v_mfma_f32_16x16x32_bf16 v[12:15], v[188:191], v[184:187], v[12:15]
	ds_write_b128 v166, v[60:63] offset:12288
	v_mfma_f32_16x16x32_bf16 v[8:11], v[192:195], v[184:187], v[8:11]
	ds_write_b128 v166, v[76:79] offset:28672
	v_mfma_f32_16x16x32_bf16 v[4:7], v[196:199], v[184:187], v[4:7]
	v_mfma_f32_16x16x32_bf16 v[0:3], v[200:203], v[184:187], v[0:3]
	s_waitcnt lgkmcnt(8)
	ds_read_b128 v[184:187], v131 offset:38912
	v_mfma_f32_16x16x32_bf16 v[92:95], v[204:207], v[172:175], v[92:95]
	v_mfma_f32_16x16x32_bf16 v[88:91], v[208:211], v[172:175], v[88:91]
	v_mfma_f32_16x16x32_bf16 v[84:87], v[212:215], v[172:175], v[84:87]
	v_mfma_f32_16x16x32_bf16 v[150:153], v[220:223], v[172:175], v[150:153]
	s_waitcnt lgkmcnt(0)
	v_mfma_f32_16x16x32_bf16 v[44:47], v[204:207], v[176:179], v[44:47]
	global_load_dwordx4 v[48:51], v116, s[100:101] offset:512
	v_mfma_f32_16x16x32_bf16 v[40:43], v[208:211], v[176:179], v[40:43]
	global_load_dwordx4 v[64:67], v118, s[98:99] offset:512
	v_mfma_f32_16x16x32_bf16 v[36:39], v[212:215], v[176:179], v[36:39]
	global_load_dwordx4 v[52:55], v117, s[100:101] offset:512
	v_mfma_f32_16x16x32_bf16 v[32:35], v[220:223], v[176:179], v[32:35]
	global_load_dwordx4 v[68:71], v119, s[98:99] offset:512
	v_mfma_f32_16x16x32_bf16 v[28:31], v[204:207], v[180:183], v[28:31]
	global_load_dwordx4 v[56:59], v97, s[100:101] offset:512
	v_mfma_f32_16x16x32_bf16 v[24:27], v[208:211], v[180:183], v[24:27]
	global_load_dwordx4 v[72:75], v103, s[98:99] offset:512
	v_mfma_f32_16x16x32_bf16 v[20:23], v[212:215], v[180:183], v[20:23]
	global_load_dwordx4 v[60:63], v101, s[100:101] offset:512
	v_mfma_f32_16x16x32_bf16 v[16:19], v[220:223], v[180:183], v[16:19]
	global_load_dwordx4 v[76:79], v105, s[98:99] offset:512
	v_mfma_f32_16x16x32_bf16 v[12:15], v[204:207], v[184:187], v[12:15]
	v_mfma_f32_16x16x32_bf16 v[8:11], v[208:211], v[184:187], v[8:11]
	v_mfma_f32_16x16x32_bf16 v[4:7], v[212:215], v[184:187], v[4:7]
	v_mfma_f32_16x16x32_bf16 v[0:3], v[220:223], v[184:187], v[0:3]
	s_setprio 0
	s_barrier
	s_add_u32 s100, s100, 0x100
	s_addc_u32 s101, s101, 0
	s_add_u32 s98, s98, 0x100
	s_addc_u32 s99, s99, 0
	s_sub_u32 s94, s94, 1
	s_cmp_lg_u32 s94, 0
	s_cbranch_scc1 .Lgm_p5_loop
	ds_read_b128 v[188:191], v132 offset:16384
	ds_read_b128 v[172:175], v133
	ds_read_b128 v[192:195], v132 offset:18432
	ds_read_b128 v[196:199], v132 offset:20480
	ds_read_b128 v[200:203], v132 offset:22528
	ds_read_b128 v[176:179], v133 offset:2048
	ds_read_b128 v[180:183], v133 offset:4096
	ds_read_b128 v[184:187], v133 offset:6144
	ds_read_b128 v[204:207], v130 offset:16384
	ds_read_b128 v[208:211], v130 offset:18432
	ds_read_b128 v[212:215], v130 offset:20480
	ds_read_b128 v[220:223], v130 offset:22528
	s_setprio 1
	s_waitcnt lgkmcnt(7)
	v_mfma_f32_16x16x32_bf16 v[92:95], v[188:191], v[172:175], v[92:95]
	v_mfma_f32_16x16x32_bf16 v[88:91], v[192:195], v[172:175], v[88:91]
	v_mfma_f32_16x16x32_bf16 v[84:87], v[196:199], v[172:175], v[84:87]
	v_mfma_f32_16x16x32_bf16 v[150:153], v[200:203], v[172:175], v[150:153]
	ds_read_b128 v[172:175], v131
	s_waitcnt lgkmcnt(5)
	v_mfma_f32_16x16x32_bf16 v[44:47], v[188:191], v[176:179], v[44:47]
	s_waitcnt vmcnt(8)
	ds_write_b128 v166, v[80:83] offset:32768
	v_mfma_f32_16x16x32_bf16 v[40:43], v[192:195], v[176:179], v[40:43]
	ds_write_b128 v166, v[138:141] offset:49152
	v_mfma_f32_16x16x32_bf16 v[36:39], v[196:199], v[176:179], v[36:39]
	ds_write_b128 v166, v[120:123] offset:36864
	v_mfma_f32_16x16x32_bf16 v[32:35], v[200:203], v[176:179], v[32:35]
	ds_read_b128 v[176:179], v131 offset:2048
	v_mfma_f32_16x16x32_bf16 v[28:31], v[188:191], v[180:183], v[28:31]
	ds_write_b128 v166, v[142:145] offset:53248
	v_mfma_f32_16x16x32_bf16 v[24:27], v[192:195], v[180:183], v[24:27]
	ds_write_b128 v166, v[124:127] offset:40960
	v_mfma_f32_16x16x32_bf16 v[20:23], v[196:199], v[180:183], v[20:23]
	ds_write_b128 v166, v[146:149] offset:57344
	v_mfma_f32_16x16x32_bf16 v[16:19], v[200:203], v[180:183], v[16:19]
	ds_read_b128 v[180:183], v131 offset:4096
	v_mfma_f32_16x16x32_bf16 v[12:15], v[188:191], v[184:187], v[12:15]
	ds_write_b128 v166, v[134:137] offset:45056
	v_mfma_f32_16x16x32_bf16 v[8:11], v[192:195], v[184:187], v[8:11]
	ds_write_b128 v166, v[168:171] offset:61440
	v_mfma_f32_16x16x32_bf16 v[4:7], v[196:199], v[184:187], v[4:7]
	v_mfma_f32_16x16x32_bf16 v[0:3], v[200:203], v[184:187], v[0:3]
	s_waitcnt lgkmcnt(8)
	ds_read_b128 v[184:187], v131 offset:6144
	v_mfma_f32_16x16x32_bf16 v[92:95], v[204:207], v[172:175], v[92:95]
	v_mfma_f32_16x16x32_bf16 v[88:91], v[208:211], v[172:175], v[88:91]
	v_mfma_f32_16x16x32_bf16 v[84:87], v[212:215], v[172:175], v[84:87]
	v_mfma_f32_16x16x32_bf16 v[150:153], v[220:223], v[172:175], v[150:153]
	s_waitcnt lgkmcnt(0)
	v_mfma_f32_16x16x32_bf16 v[44:47], v[204:207], v[176:179], v[44:47]
	global_load_dwordx4 v[80:83], v116, s[100:101] offset:384
	v_mfma_f32_16x16x32_bf16 v[40:43], v[208:211], v[176:179], v[40:43]
	global_load_dwordx4 v[138:141], v118, s[98:99] offset:384
	v_mfma_f32_16x16x32_bf16 v[36:39], v[212:215], v[176:179], v[36:39]
	global_load_dwordx4 v[120:123], v117, s[100:101] offset:384
	v_mfma_f32_16x16x32_bf16 v[32:35], v[220:223], v[176:179], v[32:35]
	global_load_dwordx4 v[142:145], v119, s[98:99] offset:384
	v_mfma_f32_16x16x32_bf16 v[28:31], v[204:207], v[180:183], v[28:31]
	global_load_dwordx4 v[124:127], v97, s[100:101] offset:384
	v_mfma_f32_16x16x32_bf16 v[24:27], v[208:211], v[180:183], v[24:27]
	global_load_dwordx4 v[146:149], v103, s[98:99] offset:384
	v_mfma_f32_16x16x32_bf16 v[20:23], v[212:215], v[180:183], v[20:23]
	global_load_dwordx4 v[134:137], v101, s[100:101] offset:384
	v_mfma_f32_16x16x32_bf16 v[16:19], v[220:223], v[180:183], v[16:19]
	global_load_dwordx4 v[168:171], v105, s[98:99] offset:384
	v_mfma_f32_16x16x32_bf16 v[12:15], v[204:207], v[184:187], v[12:15]
	v_mfma_f32_16x16x32_bf16 v[8:11], v[208:211], v[184:187], v[8:11]
	v_mfma_f32_16x16x32_bf16 v[4:7], v[212:215], v[184:187], v[4:7]
	v_mfma_f32_16x16x32_bf16 v[0:3], v[220:223], v[184:187], v[0:3]
	s_setprio 0
	s_barrier
	ds_read_b128 v[188:191], v132 offset:49152
	ds_read_b128 v[172:175], v133 offset:32768
	ds_read_b128 v[192:195], v132 offset:51200
	ds_read_b128 v[196:199], v132 offset:53248
	ds_read_b128 v[200:203], v132 offset:55296
	ds_read_b128 v[176:179], v133 offset:34816
	ds_read_b128 v[180:183], v133 offset:36864
	ds_read_b128 v[184:187], v133 offset:38912
	ds_read_b128 v[204:207], v130 offset:49152
	ds_read_b128 v[208:211], v130 offset:51200
	ds_read_b128 v[212:215], v130 offset:53248
	ds_read_b128 v[220:223], v130 offset:55296
	s_setprio 1
	s_waitcnt lgkmcnt(7)
	v_mfma_f32_16x16x32_bf16 v[92:95], v[188:191], v[172:175], v[92:95]
	v_mfma_f32_16x16x32_bf16 v[88:91], v[192:195], v[172:175], v[88:91]
	v_mfma_f32_16x16x32_bf16 v[84:87], v[196:199], v[172:175], v[84:87]
	v_mfma_f32_16x16x32_bf16 v[150:153], v[200:203], v[172:175], v[150:153]
	ds_read_b128 v[172:175], v131 offset:32768
	s_waitcnt lgkmcnt(5)
	v_mfma_f32_16x16x32_bf16 v[44:47], v[188:191], v[176:179], v[44:47]
	s_waitcnt vmcnt(8)
	ds_write_b128 v166, v[48:51]
	v_mfma_f32_16x16x32_bf16 v[40:43], v[192:195], v[176:179], v[40:43]
	ds_write_b128 v166, v[64:67] offset:16384
	v_mfma_f32_16x16x32_bf16 v[36:39], v[196:199], v[176:179], v[36:39]
	ds_write_b128 v166, v[52:55] offset:4096
	v_mfma_f32_16x16x32_bf16 v[32:35], v[200:203], v[176:179], v[32:35]
	ds_read_b128 v[176:179], v131 offset:34816
	v_mfma_f32_16x16x32_bf16 v[28:31], v[188:191], v[180:183], v[28:31]
	ds_write_b128 v166, v[68:71] offset:20480
	v_mfma_f32_16x16x32_bf16 v[24:27], v[192:195], v[180:183], v[24:27]
	ds_write_b128 v166, v[56:59] offset:8192
	v_mfma_f32_16x16x32_bf16 v[20:23], v[196:199], v[180:183], v[20:23]
	ds_write_b128 v166, v[72:75] offset:24576
	v_mfma_f32_16x16x32_bf16 v[16:19], v[200:203], v[180:183], v[16:19]
	ds_read_b128 v[180:183], v131 offset:36864
	v_mfma_f32_16x16x32_bf16 v[12:15], v[188:191], v[184:187], v[12:15]
	ds_write_b128 v166, v[60:63] offset:12288
	v_mfma_f32_16x16x32_bf16 v[8:11], v[192:195], v[184:187], v[8:11]
	ds_write_b128 v166, v[76:79] offset:28672
	v_mfma_f32_16x16x32_bf16 v[4:7], v[196:199], v[184:187], v[4:7]
	v_mfma_f32_16x16x32_bf16 v[0:3], v[200:203], v[184:187], v[0:3]
	s_waitcnt lgkmcnt(8)
	ds_read_b128 v[184:187], v131 offset:38912
	v_mfma_f32_16x16x32_bf16 v[92:95], v[204:207], v[172:175], v[92:95]
	v_mfma_f32_16x16x32_bf16 v[88:91], v[208:211], v[172:175], v[88:91]
	v_mfma_f32_16x16x32_bf16 v[84:87], v[212:215], v[172:175], v[84:87]
	v_mfma_f32_16x16x32_bf16 v[150:153], v[220:223], v[172:175], v[150:153]
	s_waitcnt lgkmcnt(0)
	v_mfma_f32_16x16x32_bf16 v[44:47], v[204:207], v[176:179], v[44:47]
	v_mfma_f32_16x16x32_bf16 v[40:43], v[208:211], v[176:179], v[40:43]
	v_mfma_f32_16x16x32_bf16 v[36:39], v[212:215], v[176:179], v[36:39]
	v_mfma_f32_16x16x32_bf16 v[32:35], v[220:223], v[176:179], v[32:35]
	v_mfma_f32_16x16x32_bf16 v[28:31], v[204:207], v[180:183], v[28:31]
	v_mfma_f32_16x16x32_bf16 v[24:27], v[208:211], v[180:183], v[24:27]
	v_mfma_f32_16x16x32_bf16 v[20:23], v[212:215], v[180:183], v[20:23]
	v_mfma_f32_16x16x32_bf16 v[16:19], v[220:223], v[180:183], v[16:19]
	v_mfma_f32_16x16x32_bf16 v[12:15], v[204:207], v[184:187], v[12:15]
	v_mfma_f32_16x16x32_bf16 v[8:11], v[208:211], v[184:187], v[8:11]
	v_mfma_f32_16x16x32_bf16 v[4:7], v[212:215], v[184:187], v[4:7]
	v_mfma_f32_16x16x32_bf16 v[0:3], v[220:223], v[184:187], v[0:3]
	s_setprio 0
	s_barrier
	ds_read_b128 v[188:191], v132 offset:16384
	ds_read_b128 v[172:175], v133
	ds_read_b128 v[192:195], v132 offset:18432
	ds_read_b128 v[196:199], v132 offset:20480
	ds_read_b128 v[200:203], v132 offset:22528
	ds_read_b128 v[176:179], v133 offset:2048
	ds_read_b128 v[180:183], v133 offset:4096
	ds_read_b128 v[184:187], v133 offset:6144
	ds_read_b128 v[204:207], v130 offset:16384
	ds_read_b128 v[208:211], v130 offset:18432
	ds_read_b128 v[212:215], v130 offset:20480
	ds_read_b128 v[220:223], v130 offset:22528
	s_setprio 1
	s_waitcnt lgkmcnt(7)
	v_mfma_f32_16x16x32_bf16 v[92:95], v[188:191], v[172:175], v[92:95]
	v_mfma_f32_16x16x32_bf16 v[88:91], v[192:195], v[172:175], v[88:91]
	v_mfma_f32_16x16x32_bf16 v[84:87], v[196:199], v[172:175], v[84:87]
	v_mfma_f32_16x16x32_bf16 v[150:153], v[200:203], v[172:175], v[150:153]
	ds_read_b128 v[172:175], v131
	s_waitcnt lgkmcnt(5)
	v_mfma_f32_16x16x32_bf16 v[44:47], v[188:191], v[176:179], v[44:47]
	s_waitcnt vmcnt(0)
	ds_write_b128 v166, v[80:83] offset:32768
	v_mfma_f32_16x16x32_bf16 v[40:43], v[192:195], v[176:179], v[40:43]
	ds_write_b128 v166, v[138:141] offset:49152
	v_mfma_f32_16x16x32_bf16 v[36:39], v[196:199], v[176:179], v[36:39]
	ds_write_b128 v166, v[120:123] offset:36864
	v_mfma_f32_16x16x32_bf16 v[32:35], v[200:203], v[176:179], v[32:35]
	ds_read_b128 v[176:179], v131 offset:2048
	v_mfma_f32_16x16x32_bf16 v[28:31], v[188:191], v[180:183], v[28:31]
	ds_write_b128 v166, v[142:145] offset:53248
	v_mfma_f32_16x16x32_bf16 v[24:27], v[192:195], v[180:183], v[24:27]
	ds_write_b128 v166, v[124:127] offset:40960
	v_mfma_f32_16x16x32_bf16 v[20:23], v[196:199], v[180:183], v[20:23]
	ds_write_b128 v166, v[146:149] offset:57344
	v_mfma_f32_16x16x32_bf16 v[16:19], v[200:203], v[180:183], v[16:19]
	ds_read_b128 v[180:183], v131 offset:4096
	v_mfma_f32_16x16x32_bf16 v[12:15], v[188:191], v[184:187], v[12:15]
	ds_write_b128 v166, v[134:137] offset:45056
	v_mfma_f32_16x16x32_bf16 v[8:11], v[192:195], v[184:187], v[8:11]
	ds_write_b128 v166, v[168:171] offset:61440
	v_mfma_f32_16x16x32_bf16 v[4:7], v[196:199], v[184:187], v[4:7]
	v_mfma_f32_16x16x32_bf16 v[0:3], v[200:203], v[184:187], v[0:3]
	s_waitcnt lgkmcnt(8)
	ds_read_b128 v[184:187], v131 offset:6144
	v_mfma_f32_16x16x32_bf16 v[92:95], v[204:207], v[172:175], v[92:95]
	v_mfma_f32_16x16x32_bf16 v[88:91], v[208:211], v[172:175], v[88:91]
	v_mfma_f32_16x16x32_bf16 v[84:87], v[212:215], v[172:175], v[84:87]
	v_mfma_f32_16x16x32_bf16 v[150:153], v[220:223], v[172:175], v[150:153]
	s_waitcnt lgkmcnt(0)
	v_mfma_f32_16x16x32_bf16 v[44:47], v[204:207], v[176:179], v[44:47]
	v_mfma_f32_16x16x32_bf16 v[40:43], v[208:211], v[176:179], v[40:43]
	v_mfma_f32_16x16x32_bf16 v[36:39], v[212:215], v[176:179], v[36:39]
	v_mfma_f32_16x16x32_bf16 v[32:35], v[220:223], v[176:179], v[32:35]
	v_mfma_f32_16x16x32_bf16 v[28:31], v[204:207], v[180:183], v[28:31]
	v_mfma_f32_16x16x32_bf16 v[24:27], v[208:211], v[180:183], v[24:27]
	v_mfma_f32_16x16x32_bf16 v[20:23], v[212:215], v[180:183], v[20:23]
	v_mfma_f32_16x16x32_bf16 v[16:19], v[220:223], v[180:183], v[16:19]
	v_mfma_f32_16x16x32_bf16 v[12:15], v[204:207], v[184:187], v[12:15]
	v_mfma_f32_16x16x32_bf16 v[8:11], v[208:211], v[184:187], v[8:11]
	v_mfma_f32_16x16x32_bf16 v[4:7], v[212:215], v[184:187], v[4:7]
	v_mfma_f32_16x16x32_bf16 v[0:3], v[220:223], v[184:187], v[0:3]
	s_setprio 0
	s_barrier
	ds_read_b128 v[188:191], v132 offset:49152
	ds_read_b128 v[172:175], v133 offset:32768
	ds_read_b128 v[192:195], v132 offset:51200
	ds_read_b128 v[196:199], v132 offset:53248
	ds_read_b128 v[200:203], v132 offset:55296
	ds_read_b128 v[176:179], v133 offset:34816
	ds_read_b128 v[180:183], v133 offset:36864
	ds_read_b128 v[184:187], v133 offset:38912
	ds_read_b128 v[204:207], v130 offset:49152
	ds_read_b128 v[208:211], v130 offset:51200
	ds_read_b128 v[212:215], v130 offset:53248
	ds_read_b128 v[220:223], v130 offset:55296
	s_setprio 1
	s_waitcnt lgkmcnt(7)
	v_mfma_f32_16x16x32_bf16 v[92:95], v[188:191], v[172:175], v[92:95]
	v_mfma_f32_16x16x32_bf16 v[88:91], v[192:195], v[172:175], v[88:91]
	v_mfma_f32_16x16x32_bf16 v[84:87], v[196:199], v[172:175], v[84:87]
	v_mfma_f32_16x16x32_bf16 v[150:153], v[200:203], v[172:175], v[150:153]
	ds_read_b128 v[172:175], v131 offset:32768
	s_waitcnt lgkmcnt(5)
	v_mfma_f32_16x16x32_bf16 v[44:47], v[188:191], v[176:179], v[44:47]
	v_mfma_f32_16x16x32_bf16 v[40:43], v[192:195], v[176:179], v[40:43]
	v_mfma_f32_16x16x32_bf16 v[36:39], v[196:199], v[176:179], v[36:39]
	v_mfma_f32_16x16x32_bf16 v[32:35], v[200:203], v[176:179], v[32:35]
	ds_read_b128 v[176:179], v131 offset:34816
	v_mfma_f32_16x16x32_bf16 v[28:31], v[188:191], v[180:183], v[28:31]
	v_mfma_f32_16x16x32_bf16 v[24:27], v[192:195], v[180:183], v[24:27]
	v_mfma_f32_16x16x32_bf16 v[20:23], v[196:199], v[180:183], v[20:23]
	v_mfma_f32_16x16x32_bf16 v[16:19], v[200:203], v[180:183], v[16:19]
	ds_read_b128 v[180:183], v131 offset:36864
	v_mfma_f32_16x16x32_bf16 v[12:15], v[188:191], v[184:187], v[12:15]
	v_mfma_f32_16x16x32_bf16 v[8:11], v[192:195], v[184:187], v[8:11]
	v_mfma_f32_16x16x32_bf16 v[4:7], v[196:199], v[184:187], v[4:7]
	v_mfma_f32_16x16x32_bf16 v[0:3], v[200:203], v[184:187], v[0:3]
	ds_read_b128 v[184:187], v131 offset:38912
	s_waitcnt lgkmcnt(3)
	v_mfma_f32_16x16x32_bf16 v[92:95], v[204:207], v[172:175], v[92:95]
	v_mfma_f32_16x16x32_bf16 v[88:91], v[208:211], v[172:175], v[88:91]
	v_mfma_f32_16x16x32_bf16 v[84:87], v[212:215], v[172:175], v[84:87]
	v_mfma_f32_16x16x32_bf16 v[150:153], v[220:223], v[172:175], v[150:153]
	s_waitcnt lgkmcnt(0)
	v_mfma_f32_16x16x32_bf16 v[44:47], v[204:207], v[176:179], v[44:47]
	v_mfma_f32_16x16x32_bf16 v[40:43], v[208:211], v[176:179], v[40:43]
	v_mfma_f32_16x16x32_bf16 v[36:39], v[212:215], v[176:179], v[36:39]
	v_mfma_f32_16x16x32_bf16 v[32:35], v[220:223], v[176:179], v[32:35]
	v_mfma_f32_16x16x32_bf16 v[28:31], v[204:207], v[180:183], v[28:31]
	v_mfma_f32_16x16x32_bf16 v[24:27], v[208:211], v[180:183], v[24:27]
	v_mfma_f32_16x16x32_bf16 v[20:23], v[212:215], v[180:183], v[20:23]
	v_mfma_f32_16x16x32_bf16 v[16:19], v[220:223], v[180:183], v[16:19]
	v_mfma_f32_16x16x32_bf16 v[12:15], v[204:207], v[184:187], v[12:15]
	v_mfma_f32_16x16x32_bf16 v[8:11], v[208:211], v[184:187], v[8:11]
	v_mfma_f32_16x16x32_bf16 v[4:7], v[212:215], v[184:187], v[4:7]
	v_mfma_f32_16x16x32_bf16 v[0:3], v[220:223], v[184:187], v[0:3]
	s_setprio 0
	s_nop 7
	v_readlane_b32 s44, v252, 8
	v_readlane_b32 s45, v252, 9
	v_add_u32_e32 v50, s5, v167
	v_readlane_b32 s46, v252, 10
	v_readlane_b32 s47, v252, 11
	s_mov_b64 s[12:13], s[44:45]
	v_add_u32_e32 v48, 0xffffc000, v50
	v_ashrrev_i32_e32 v51, 31, v50
	v_cmp_gt_i32_e32 vcc, s18, v50
	s_mov_b64 s[14:15], s[46:47]
	v_mov_b32_e32 v76, s15
	v_cndmask_b32_e32 v49, 0, v51, vcc
	v_cndmask_b32_e32 v48, v48, v50, vcc
	v_mov_b32_e32 v77, s13
	v_mov_b32_e32 v78, s14
	v_mov_b32_e32 v79, s12
	s_ashr_i32 s5, s4, 31
	v_cndmask_b32_e32 v53, v76, v77, vcc
	v_cndmask_b32_e32 v52, v78, v79, vcc
	v_lshlrev_b64 v[48:49], 12, v[48:49]
	v_lshl_add_u64 v[48:49], v[52:53], 0, v[48:49]
	s_lshl_b64 s[4:5], s[4:5], 2
	v_lshl_add_u64 v[48:49], v[48:49], 0, s[4:5]
	v_lshlrev_b32_e32 v110, 2, v102
	v_lshl_add_u64 v[52:53], v[48:49], 0, v[110:111]
	v_lshlrev_b32_e32 v48, 2, v104
	v_mov_b32_e32 v49, v111
	v_lshl_add_u64 v[64:65], v[52:53], 0, v[48:49]
	global_load_dwordx4 v[52:55], v[64:65], off
	global_load_dwordx4 v[56:59], v[64:65], off offset:64
	global_load_dwordx4 v[60:63], v[64:65], off offset:128
	s_nop 0
	global_load_dwordx4 v[64:67], v[64:65], off offset:192
	v_readlane_b32 s48, v252, 12
	v_readlane_b32 s49, v252, 13
	v_readlane_b32 s50, v252, 14
	v_readlane_b32 s51, v252, 15
	v_readlane_b32 s52, v252, 16
	v_readlane_b32 s53, v252, 17
	v_readlane_b32 s54, v252, 18
	v_readlane_b32 s55, v252, 19
	v_readlane_b32 s56, v252, 20
	v_readlane_b32 s57, v252, 21
	v_readlane_b32 s58, v252, 22
	v_readlane_b32 s59, v252, 23
	v_or_b32_e32 v68, 16, v50
	v_add_u32_e32 v72, 0xffffc010, v50
	v_ashrrev_i32_e32 v69, 31, v68
	v_readlane_b32 s44, v251, 40
	v_cmp_gt_i32_e32 vcc, s18, v68
	v_lshlrev_b64 v[70:71], 12, v[50:51]
	v_readlane_b32 s52, v251, 48
	v_readlane_b32 s53, v251, 49
	v_cndmask_b32_e32 v73, 0, v69, vcc
	v_cndmask_b32_e32 v72, v72, v68, vcc
	v_lshl_add_u64 v[70:71], s[52:53], 0, v[70:71]
	v_cndmask_b32_e32 v75, v76, v77, vcc
	v_cndmask_b32_e32 v74, v78, v79, vcc
	v_lshlrev_b64 v[72:73], 12, v[72:73]
	v_lshl_add_u64 v[70:71], v[70:71], 0, s[4:5]
	v_lshl_add_u64 v[72:73], v[74:75], 0, v[72:73]
	v_lshl_add_u64 v[70:71], v[70:71], 0, v[110:111]
	v_lshl_add_u64 v[72:73], v[72:73], 0, s[4:5]
	v_lshl_add_u64 v[70:71], v[70:71], 0, v[48:49]
	v_lshl_add_u64 v[72:73], v[72:73], 0, v[110:111]
	v_lshl_add_u64 v[72:73], v[72:73], 0, v[48:49]
	v_add_u32_e32 v51, 0xffffc020, v50
	v_lshlrev_b64 v[68:69], 12, v[68:69]
	v_lshl_add_u64 v[68:69], s[52:53], 0, v[68:69]
	v_lshl_add_u64 v[68:69], v[68:69], 0, s[4:5]
	v_lshl_add_u64 v[68:69], v[68:69], 0, v[110:111]
	v_lshl_add_u64 v[68:69], v[68:69], 0, v[48:49]
	s_mov_b32 s8, 0
	v_readlane_b32 s45, v251, 41
	v_readlane_b32 s46, v251, 42
	v_readlane_b32 s47, v251, 43
	v_readlane_b32 s48, v251, 44
	v_readlane_b32 s49, v251, 45
	v_readlane_b32 s50, v251, 46
	v_readlane_b32 s51, v251, 47
	v_readlane_b32 s54, v251, 50
	v_readlane_b32 s55, v251, 51
	v_readlane_b32 s56, v251, 52
	v_readlane_b32 s57, v251, 53
	v_readlane_b32 s58, v251, 54
	v_readlane_b32 s59, v251, 55
	s_waitcnt vmcnt(3)
	v_pk_add_f32 v[52:53], v[92:93], v[52:53]
	v_pk_add_f32 v[54:55], v[94:95], v[54:55]
	s_waitcnt vmcnt(2)
	v_pk_add_f32 v[56:57], v[88:89], v[56:57]
	v_pk_add_f32 v[58:59], v[90:91], v[58:59]
	s_waitcnt vmcnt(1)
	v_pk_add_f32 v[60:61], v[84:85], v[60:61]
	v_pk_add_f32 v[62:63], v[86:87], v[62:63]
	s_waitcnt vmcnt(0)
	v_pk_add_f32 v[64:65], v[150:151], v[64:65]
	v_pk_add_f32 v[66:67], v[152:153], v[66:67]
	global_store_dwordx4 v[70:71], v[52:55], off
	global_store_dwordx4 v[70:71], v[56:59], off offset:64
	global_store_dwordx4 v[70:71], v[60:63], off offset:128
	global_store_dwordx4 v[70:71], v[64:67], off offset:192
	global_load_dwordx4 v[52:55], v[72:73], off
	s_nop 0
	global_load_dwordx4 v[56:59], v[72:73], off offset:64
	global_load_dwordx4 v[60:63], v[72:73], off offset:128
	global_load_dwordx4 v[64:67], v[72:73], off offset:192
	v_or_b32_e32 v70, 32, v50
	v_ashrrev_i32_e32 v71, 31, v70
	v_cmp_gt_i32_e32 vcc, s18, v70
	s_waitcnt vmcnt(3)
	v_pk_add_f32 v[44:45], v[44:45], v[52:53]
	v_cndmask_b32_e32 v73, 0, v71, vcc
	v_cndmask_b32_e32 v72, v51, v70, vcc
	v_cndmask_b32_e32 v75, v76, v77, vcc
	v_cndmask_b32_e32 v74, v78, v79, vcc
	v_lshlrev_b64 v[72:73], 12, v[72:73]
	v_lshl_add_u64 v[72:73], v[74:75], 0, v[72:73]
	v_lshl_add_u64 v[72:73], v[72:73], 0, s[4:5]
	v_lshl_add_u64 v[72:73], v[72:73], 0, v[110:111]
	v_pk_add_f32 v[46:47], v[46:47], v[54:55]
	v_lshl_add_u64 v[72:73], v[72:73], 0, v[48:49]
	s_waitcnt vmcnt(2)
	v_pk_add_f32 v[40:41], v[40:41], v[56:57]
	v_pk_add_f32 v[42:43], v[42:43], v[58:59]
	s_waitcnt vmcnt(1)
	v_pk_add_f32 v[36:37], v[36:37], v[60:61]
	v_pk_add_f32 v[38:39], v[38:39], v[62:63]
	s_waitcnt vmcnt(0)
	v_pk_add_f32 v[32:33], v[32:33], v[64:65]
	v_pk_add_f32 v[34:35], v[34:35], v[66:67]
	global_store_dwordx4 v[68:69], v[44:47], off
	global_store_dwordx4 v[68:69], v[40:43], off offset:64
	global_store_dwordx4 v[68:69], v[36:39], off offset:128
	global_store_dwordx4 v[68:69], v[32:35], off offset:192
	global_load_dwordx4 v[32:35], v[72:73], off
	s_nop 0
	global_load_dwordx4 v[36:39], v[72:73], off offset:64
	global_load_dwordx4 v[40:43], v[72:73], off offset:128
	global_load_dwordx4 v[44:47], v[72:73], off offset:192
	v_or_b32_e32 v52, 48, v50
	v_add_u32_e32 v54, 0xffffc030, v50
	v_ashrrev_i32_e32 v53, 31, v52
	v_cmp_gt_i32_e32 vcc, s18, v52
	v_lshlrev_b64 v[50:51], 12, v[70:71]
	v_lshl_add_u64 v[50:51], s[52:53], 0, v[50:51]
	v_cndmask_b32_e32 v55, 0, v53, vcc
	v_cndmask_b32_e32 v54, v54, v52, vcc
	v_cndmask_b32_e32 v57, v76, v77, vcc
	v_cndmask_b32_e32 v56, v78, v79, vcc
	v_lshlrev_b64 v[54:55], 12, v[54:55]
	v_lshl_add_u64 v[50:51], v[50:51], 0, s[4:5]
	v_lshl_add_u64 v[54:55], v[56:57], 0, v[54:55]
	v_lshl_add_u64 v[50:51], v[50:51], 0, v[110:111]
	v_lshl_add_u64 v[54:55], v[54:55], 0, s[4:5]
	v_lshl_add_u64 v[50:51], v[50:51], 0, v[48:49]
	v_lshl_add_u64 v[54:55], v[54:55], 0, v[110:111]
	v_lshl_add_u64 v[54:55], v[54:55], 0, v[48:49]
	s_waitcnt vmcnt(3)
	v_pk_add_f32 v[28:29], v[28:29], v[32:33]
	v_pk_add_f32 v[30:31], v[30:31], v[34:35]
	s_waitcnt vmcnt(2)
	v_pk_add_f32 v[24:25], v[24:25], v[36:37]
	v_pk_add_f32 v[26:27], v[26:27], v[38:39]
	s_waitcnt vmcnt(1)
	v_pk_add_f32 v[20:21], v[20:21], v[40:41]
	v_pk_add_f32 v[22:23], v[22:23], v[42:43]
	s_waitcnt vmcnt(0)
	v_pk_add_f32 v[16:17], v[16:17], v[44:45]
	v_pk_add_f32 v[18:19], v[18:19], v[46:47]
	global_store_dwordx4 v[50:51], v[28:31], off
	global_store_dwordx4 v[50:51], v[24:27], off offset:64
	global_store_dwordx4 v[50:51], v[20:23], off offset:128
	global_store_dwordx4 v[50:51], v[16:19], off offset:192
	global_load_dwordx4 v[16:19], v[54:55], off
	s_nop 0
	global_load_dwordx4 v[20:23], v[54:55], off offset:64
	global_load_dwordx4 v[24:27], v[54:55], off offset:128
	global_load_dwordx4 v[28:31], v[54:55], off offset:192
	v_lshlrev_b64 v[32:33], 12, v[52:53]
	v_lshl_add_u64 v[32:33], s[52:53], 0, v[32:33]
	v_lshl_add_u64 v[32:33], v[32:33], 0, s[4:5]
	v_lshl_add_u64 v[32:33], v[32:33], 0, v[110:111]
	v_lshl_add_u64 v[32:33], v[32:33], 0, v[48:49]
	s_waitcnt vmcnt(3)
	v_pk_add_f32 v[12:13], v[12:13], v[16:17]
	v_pk_add_f32 v[14:15], v[14:15], v[18:19]
	s_waitcnt vmcnt(2)
	v_pk_add_f32 v[8:9], v[8:9], v[20:21]
	v_pk_add_f32 v[10:11], v[10:11], v[22:23]
	s_waitcnt vmcnt(1)
	v_pk_add_f32 v[4:5], v[4:5], v[24:25]
	v_pk_add_f32 v[6:7], v[6:7], v[26:27]
	s_waitcnt vmcnt(0)
	v_pk_add_f32 v[0:1], v[0:1], v[28:29]
	v_pk_add_f32 v[2:3], v[2:3], v[30:31]
	global_store_dwordx4 v[32:33], v[12:15], off
	global_store_dwordx4 v[32:33], v[8:11], off offset:64
	global_store_dwordx4 v[32:33], v[4:7], off offset:128
	global_store_dwordx4 v[32:33], v[0:3], off offset:192
	s_mov_b64 s[4:5], -1
	s_cmp_gt_i32 s8, 3
	s_mov_b64 s[6:7], -1
	s_cbranch_scc1 .LBB0_681

.Lgm_p7_loop:
	ds_read_b128 v[216:219], v132 offset:16384
	ds_read_b128 v[200:203], v133
	ds_read_b128 v[220:223], v132 offset:18432
	ds_read_b128 v[224:227], v132 offset:20480
	ds_read_b128 v[228:231], v132 offset:22528
	ds_read_b128 v[204:207], v133 offset:2048
	ds_read_b128 v[208:211], v133 offset:4096
	ds_read_b128 v[212:215], v133 offset:6144
	s_setprio 1
	s_waitcnt lgkmcnt(3)
	v_mfma_f32_16x16x32_bf16 v[0:3], v[216:219], v[200:203], v[0:3]
	ds_read_b128 v[138:141], v130 offset:16384
	v_mfma_f32_16x16x32_bf16 v[4:7], v[220:223], v[200:203], v[4:7]
	ds_read_b128 v[232:235], v131
	v_mfma_f32_16x16x32_bf16 v[8:11], v[224:227], v[200:203], v[8:11]
	ds_read_b128 v[142:145], v130 offset:18432
	v_mfma_f32_16x16x32_bf16 v[12:15], v[228:231], v[200:203], v[12:15]
	ds_read_b128 v[146:149], v130 offset:20480
	s_waitcnt lgkmcnt(4)
	v_mfma_f32_16x16x32_bf16 v[16:19], v[216:219], v[204:207], v[16:19]
	ds_read_b128 v[150:153], v130 offset:22528
	v_mfma_f32_16x16x32_bf16 v[20:23], v[220:223], v[204:207], v[20:23]
	ds_read_b128 v[236:239], v131 offset:2048
	v_mfma_f32_16x16x32_bf16 v[24:27], v[224:227], v[204:207], v[24:27]
	ds_read_b128 v[240:243], v131 offset:4096
	v_mfma_f32_16x16x32_bf16 v[28:31], v[228:231], v[204:207], v[28:31]
	ds_read_b128 v[244:247], v131 offset:6144
	v_mfma_f32_16x16x32_bf16 v[32:35], v[216:219], v[208:211], v[32:35]
	s_waitcnt vmcnt(8)
	ds_write_b128 v166, v[168:171] offset:32768
	v_mfma_f32_16x16x32_bf16 v[36:39], v[220:223], v[208:211], v[36:39]
	ds_write_b128 v166, v[184:187] offset:49152
	v_mfma_f32_16x16x32_bf16 v[40:43], v[224:227], v[208:211], v[40:43]
	ds_write_b128 v166, v[172:175] offset:36864
	v_mfma_f32_16x16x32_bf16 v[44:47], v[228:231], v[208:211], v[44:47]
	ds_write_b128 v166, v[188:191] offset:53248
	v_mfma_f32_16x16x32_bf16 v[48:51], v[216:219], v[212:215], v[48:51]
	ds_write_b128 v166, v[176:179] offset:40960
	v_mfma_f32_16x16x32_bf16 v[52:55], v[220:223], v[212:215], v[52:55]
	ds_write_b128 v166, v[192:195] offset:57344
	v_mfma_f32_16x16x32_bf16 v[56:59], v[224:227], v[212:215], v[56:59]
	ds_write_b128 v166, v[180:183] offset:45056
	v_mfma_f32_16x16x32_bf16 v[60:63], v[228:231], v[212:215], v[60:63]
	s_waitcnt lgkmcnt(8)
	ds_write_b128 v166, v[196:199] offset:61440
	v_mfma_f32_16x16x32_bf16 v[0:3], v[138:141], v[232:235], v[0:3]
	v_mfma_f32_16x16x32_bf16 v[4:7], v[142:145], v[232:235], v[4:7]
	v_mfma_f32_16x16x32_bf16 v[8:11], v[146:149], v[232:235], v[8:11]
	v_mfma_f32_16x16x32_bf16 v[12:15], v[150:153], v[232:235], v[12:15]
	s_waitcnt lgkmcnt(8)
	v_mfma_f32_16x16x32_bf16 v[16:19], v[138:141], v[236:239], v[16:19]
	s_waitcnt lgkmcnt(0)
	global_load_dwordx4 v[168:171], v126, s[64:65] offset:384
	v_mfma_f32_16x16x32_bf16 v[20:23], v[142:145], v[236:239], v[20:23]
	global_load_dwordx4 v[184:187], v128, s[66:67] offset:384
	v_mfma_f32_16x16x32_bf16 v[24:27], v[146:149], v[236:239], v[24:27]
	global_load_dwordx4 v[172:175], v127, s[64:65] offset:384
	v_mfma_f32_16x16x32_bf16 v[28:31], v[150:153], v[236:239], v[28:31]
	global_load_dwordx4 v[188:191], v129, s[66:67] offset:384
	v_mfma_f32_16x16x32_bf16 v[32:35], v[138:141], v[240:243], v[32:35]
	global_load_dwordx4 v[176:179], v137, s[64:65] offset:384
	v_mfma_f32_16x16x32_bf16 v[36:39], v[142:145], v[240:243], v[36:39]
	global_load_dwordx4 v[192:195], v161, s[66:67] offset:384
	v_mfma_f32_16x16x32_bf16 v[40:43], v[146:149], v[240:243], v[40:43]
	global_load_dwordx4 v[180:183], v117, s[64:65] offset:384
	v_mfma_f32_16x16x32_bf16 v[44:47], v[150:153], v[240:243], v[44:47]
	global_load_dwordx4 v[196:199], v162, s[66:67] offset:384
	v_mfma_f32_16x16x32_bf16 v[48:51], v[138:141], v[244:247], v[48:51]
	v_mfma_f32_16x16x32_bf16 v[52:55], v[142:145], v[244:247], v[52:55]
	v_mfma_f32_16x16x32_bf16 v[56:59], v[146:149], v[244:247], v[56:59]
	v_mfma_f32_16x16x32_bf16 v[60:63], v[150:153], v[244:247], v[60:63]
	s_setprio 0
	s_barrier
	ds_read_b128 v[216:219], v132 offset:49152
	ds_read_b128 v[200:203], v133 offset:32768
	ds_read_b128 v[220:223], v132 offset:51200
	ds_read_b128 v[224:227], v132 offset:53248
	ds_read_b128 v[228:231], v132 offset:55296
	ds_read_b128 v[204:207], v133 offset:34816
	ds_read_b128 v[208:211], v133 offset:36864
	ds_read_b128 v[212:215], v133 offset:38912
	s_setprio 1
	s_waitcnt lgkmcnt(3)
	v_mfma_f32_16x16x32_bf16 v[0:3], v[216:219], v[200:203], v[0:3]
	ds_read_b128 v[138:141], v130 offset:49152
	v_mfma_f32_16x16x32_bf16 v[4:7], v[220:223], v[200:203], v[4:7]
	ds_read_b128 v[232:235], v131 offset:32768
	v_mfma_f32_16x16x32_bf16 v[8:11], v[224:227], v[200:203], v[8:11]
	ds_read_b128 v[142:145], v130 offset:51200
	v_mfma_f32_16x16x32_bf16 v[12:15], v[228:231], v[200:203], v[12:15]
	ds_read_b128 v[146:149], v130 offset:53248
	s_waitcnt lgkmcnt(4)
	v_mfma_f32_16x16x32_bf16 v[16:19], v[216:219], v[204:207], v[16:19]
	ds_read_b128 v[150:153], v130 offset:55296
	v_mfma_f32_16x16x32_bf16 v[20:23], v[220:223], v[204:207], v[20:23]
	ds_read_b128 v[236:239], v131 offset:34816
	v_mfma_f32_16x16x32_bf16 v[24:27], v[224:227], v[204:207], v[24:27]
	ds_read_b128 v[240:243], v131 offset:36864
	v_mfma_f32_16x16x32_bf16 v[28:31], v[228:231], v[204:207], v[28:31]
	ds_read_b128 v[244:247], v131 offset:38912
	v_mfma_f32_16x16x32_bf16 v[32:35], v[216:219], v[208:211], v[32:35]
	s_waitcnt vmcnt(8)
	ds_write_b128 v166, v[64:67]
	v_mfma_f32_16x16x32_bf16 v[36:39], v[220:223], v[208:211], v[36:39]
	ds_write_b128 v166, v[80:83] offset:16384
	v_mfma_f32_16x16x32_bf16 v[40:43], v[224:227], v[208:211], v[40:43]
	ds_write_b128 v166, v[68:71] offset:4096
	v_mfma_f32_16x16x32_bf16 v[44:47], v[228:231], v[208:211], v[44:47]
	ds_write_b128 v166, v[84:87] offset:20480
	v_mfma_f32_16x16x32_bf16 v[48:51], v[216:219], v[212:215], v[48:51]
	ds_write_b128 v166, v[72:75] offset:8192
	v_mfma_f32_16x16x32_bf16 v[52:55], v[220:223], v[212:215], v[52:55]
	ds_write_b128 v166, v[88:91] offset:24576
	v_mfma_f32_16x16x32_bf16 v[56:59], v[224:227], v[212:215], v[56:59]
	ds_write_b128 v166, v[76:79] offset:12288
	v_mfma_f32_16x16x32_bf16 v[60:63], v[228:231], v[212:215], v[60:63]
	s_waitcnt lgkmcnt(8)
	ds_write_b128 v166, v[92:95] offset:28672
	v_mfma_f32_16x16x32_bf16 v[0:3], v[138:141], v[232:235], v[0:3]
	v_mfma_f32_16x16x32_bf16 v[4:7], v[142:145], v[232:235], v[4:7]
	v_mfma_f32_16x16x32_bf16 v[8:11], v[146:149], v[232:235], v[8:11]
	v_mfma_f32_16x16x32_bf16 v[12:15], v[150:153], v[232:235], v[12:15]
	s_waitcnt lgkmcnt(8)
	v_mfma_f32_16x16x32_bf16 v[16:19], v[138:141], v[236:239], v[16:19]
	s_waitcnt lgkmcnt(0)
	global_load_dwordx4 v[64:67], v126, s[64:65] offset:512
	v_mfma_f32_16x16x32_bf16 v[20:23], v[142:145], v[236:239], v[20:23]
	global_load_dwordx4 v[80:83], v128, s[66:67] offset:512
	v_mfma_f32_16x16x32_bf16 v[24:27], v[146:149], v[236:239], v[24:27]
	global_load_dwordx4 v[68:71], v127, s[64:65] offset:512
	v_mfma_f32_16x16x32_bf16 v[28:31], v[150:153], v[236:239], v[28:31]
	global_load_dwordx4 v[84:87], v129, s[66:67] offset:512
	v_mfma_f32_16x16x32_bf16 v[32:35], v[138:141], v[240:243], v[32:35]
	global_load_dwordx4 v[72:75], v137, s[64:65] offset:512
	v_mfma_f32_16x16x32_bf16 v[36:39], v[142:145], v[240:243], v[36:39]
	global_load_dwordx4 v[88:91], v161, s[66:67] offset:512
	v_mfma_f32_16x16x32_bf16 v[40:43], v[146:149], v[240:243], v[40:43]
	global_load_dwordx4 v[76:79], v117, s[64:65] offset:512
	v_mfma_f32_16x16x32_bf16 v[44:47], v[150:153], v[240:243], v[44:47]
	global_load_dwordx4 v[92:95], v162, s[66:67] offset:512
	v_mfma_f32_16x16x32_bf16 v[48:51], v[138:141], v[244:247], v[48:51]
	v_mfma_f32_16x16x32_bf16 v[52:55], v[142:145], v[244:247], v[52:55]
	v_mfma_f32_16x16x32_bf16 v[56:59], v[146:149], v[244:247], v[56:59]
	v_mfma_f32_16x16x32_bf16 v[60:63], v[150:153], v[244:247], v[60:63]
	s_setprio 0
	s_barrier
	s_add_u32 s64, s64, 0x100
	s_addc_u32 s65, s65, 0
	s_add_u32 s66, s66, 0x100
	s_addc_u32 s67, s67, 0
	s_sub_u32 s68, s68, 1
	s_cmp_lg_u32 s68, 0
	s_cbranch_scc1 .Lgm_p7_loop
	ds_read_b128 v[216:219], v132 offset:16384
	ds_read_b128 v[200:203], v133
	ds_read_b128 v[220:223], v132 offset:18432
	ds_read_b128 v[224:227], v132 offset:20480
	ds_read_b128 v[228:231], v132 offset:22528
	ds_read_b128 v[204:207], v133 offset:2048
	ds_read_b128 v[208:211], v133 offset:4096
	ds_read_b128 v[212:215], v133 offset:6144
	s_setprio 1
	s_waitcnt lgkmcnt(3)
	v_mfma_f32_16x16x32_bf16 v[0:3], v[216:219], v[200:203], v[0:3]
	ds_read_b128 v[138:141], v130 offset:16384
	v_mfma_f32_16x16x32_bf16 v[4:7], v[220:223], v[200:203], v[4:7]
	ds_read_b128 v[232:235], v131
	v_mfma_f32_16x16x32_bf16 v[8:11], v[224:227], v[200:203], v[8:11]
	ds_read_b128 v[142:145], v130 offset:18432
	v_mfma_f32_16x16x32_bf16 v[12:15], v[228:231], v[200:203], v[12:15]
	ds_read_b128 v[146:149], v130 offset:20480
	s_waitcnt lgkmcnt(4)
	v_mfma_f32_16x16x32_bf16 v[16:19], v[216:219], v[204:207], v[16:19]
	ds_read_b128 v[150:153], v130 offset:22528
	v_mfma_f32_16x16x32_bf16 v[20:23], v[220:223], v[204:207], v[20:23]
	ds_read_b128 v[236:239], v131 offset:2048
	v_mfma_f32_16x16x32_bf16 v[24:27], v[224:227], v[204:207], v[24:27]
	ds_read_b128 v[240:243], v131 offset:4096
	v_mfma_f32_16x16x32_bf16 v[28:31], v[228:231], v[204:207], v[28:31]
	ds_read_b128 v[244:247], v131 offset:6144
	v_mfma_f32_16x16x32_bf16 v[32:35], v[216:219], v[208:211], v[32:35]
	s_waitcnt vmcnt(8)
	ds_write_b128 v166, v[168:171] offset:32768
	v_mfma_f32_16x16x32_bf16 v[36:39], v[220:223], v[208:211], v[36:39]
	ds_write_b128 v166, v[184:187] offset:49152
	v_mfma_f32_16x16x32_bf16 v[40:43], v[224:227], v[208:211], v[40:43]
	ds_write_b128 v166, v[172:175] offset:36864
	v_mfma_f32_16x16x32_bf16 v[44:47], v[228:231], v[208:211], v[44:47]
	ds_write_b128 v166, v[188:191] offset:53248
	v_mfma_f32_16x16x32_bf16 v[48:51], v[216:219], v[212:215], v[48:51]
	ds_write_b128 v166, v[176:179] offset:40960
	v_mfma_f32_16x16x32_bf16 v[52:55], v[220:223], v[212:215], v[52:55]
	ds_write_b128 v166, v[192:195] offset:57344
	v_mfma_f32_16x16x32_bf16 v[56:59], v[224:227], v[212:215], v[56:59]
	ds_write_b128 v166, v[180:183] offset:45056
	v_mfma_f32_16x16x32_bf16 v[60:63], v[228:231], v[212:215], v[60:63]
	s_waitcnt lgkmcnt(8)
	ds_write_b128 v166, v[196:199] offset:61440
	v_mfma_f32_16x16x32_bf16 v[0:3], v[138:141], v[232:235], v[0:3]
	v_mfma_f32_16x16x32_bf16 v[4:7], v[142:145], v[232:235], v[4:7]
	v_mfma_f32_16x16x32_bf16 v[8:11], v[146:149], v[232:235], v[8:11]
	v_mfma_f32_16x16x32_bf16 v[12:15], v[150:153], v[232:235], v[12:15]
	s_waitcnt lgkmcnt(8)
	v_mfma_f32_16x16x32_bf16 v[16:19], v[138:141], v[236:239], v[16:19]
	s_waitcnt lgkmcnt(0)
	global_load_dwordx4 v[168:171], v126, s[64:65] offset:384
	v_mfma_f32_16x16x32_bf16 v[20:23], v[142:145], v[236:239], v[20:23]
	global_load_dwordx4 v[184:187], v128, s[66:67] offset:384
	v_mfma_f32_16x16x32_bf16 v[24:27], v[146:149], v[236:239], v[24:27]
	global_load_dwordx4 v[172:175], v127, s[64:65] offset:384
	v_mfma_f32_16x16x32_bf16 v[28:31], v[150:153], v[236:239], v[28:31]
	global_load_dwordx4 v[188:191], v129, s[66:67] offset:384
	v_mfma_f32_16x16x32_bf16 v[32:35], v[138:141], v[240:243], v[32:35]
	global_load_dwordx4 v[176:179], v137, s[64:65] offset:384
	v_mfma_f32_16x16x32_bf16 v[36:39], v[142:145], v[240:243], v[36:39]
	global_load_dwordx4 v[192:195], v161, s[66:67] offset:384
	v_mfma_f32_16x16x32_bf16 v[40:43], v[146:149], v[240:243], v[40:43]
	global_load_dwordx4 v[180:183], v117, s[64:65] offset:384
	v_mfma_f32_16x16x32_bf16 v[44:47], v[150:153], v[240:243], v[44:47]
	global_load_dwordx4 v[196:199], v162, s[66:67] offset:384
	v_mfma_f32_16x16x32_bf16 v[48:51], v[138:141], v[244:247], v[48:51]
	v_mfma_f32_16x16x32_bf16 v[52:55], v[142:145], v[244:247], v[52:55]
	v_mfma_f32_16x16x32_bf16 v[56:59], v[146:149], v[244:247], v[56:59]
	v_mfma_f32_16x16x32_bf16 v[60:63], v[150:153], v[244:247], v[60:63]
	s_setprio 0
	s_barrier
	ds_read_b128 v[216:219], v132 offset:49152
	ds_read_b128 v[200:203], v133 offset:32768
	ds_read_b128 v[220:223], v132 offset:51200
	ds_read_b128 v[224:227], v132 offset:53248
	ds_read_b128 v[228:231], v132 offset:55296
	ds_read_b128 v[204:207], v133 offset:34816
	ds_read_b128 v[208:211], v133 offset:36864
	ds_read_b128 v[212:215], v133 offset:38912
	s_setprio 1
	s_waitcnt lgkmcnt(3)
	v_mfma_f32_16x16x32_bf16 v[0:3], v[216:219], v[200:203], v[0:3]
	ds_read_b128 v[138:141], v130 offset:49152
	v_mfma_f32_16x16x32_bf16 v[4:7], v[220:223], v[200:203], v[4:7]
	ds_read_b128 v[232:235], v131 offset:32768
	v_mfma_f32_16x16x32_bf16 v[8:11], v[224:227], v[200:203], v[8:11]
	ds_read_b128 v[142:145], v130 offset:51200
	v_mfma_f32_16x16x32_bf16 v[12:15], v[228:231], v[200:203], v[12:15]
	ds_read_b128 v[146:149], v130 offset:53248
	s_waitcnt lgkmcnt(4)
	v_mfma_f32_16x16x32_bf16 v[16:19], v[216:219], v[204:207], v[16:19]
	ds_read_b128 v[150:153], v130 offset:55296
	v_mfma_f32_16x16x32_bf16 v[20:23], v[220:223], v[204:207], v[20:23]
	ds_read_b128 v[236:239], v131 offset:34816
	v_mfma_f32_16x16x32_bf16 v[24:27], v[224:227], v[204:207], v[24:27]
	ds_read_b128 v[240:243], v131 offset:36864
	v_mfma_f32_16x16x32_bf16 v[28:31], v[228:231], v[204:207], v[28:31]
	ds_read_b128 v[244:247], v131 offset:38912
	v_mfma_f32_16x16x32_bf16 v[32:35], v[216:219], v[208:211], v[32:35]
	s_waitcnt vmcnt(8)
	ds_write_b128 v166, v[64:67]
	v_mfma_f32_16x16x32_bf16 v[36:39], v[220:223], v[208:211], v[36:39]
	ds_write_b128 v166, v[80:83] offset:16384
	v_mfma_f32_16x16x32_bf16 v[40:43], v[224:227], v[208:211], v[40:43]
	ds_write_b128 v166, v[68:71] offset:4096
	v_mfma_f32_16x16x32_bf16 v[44:47], v[228:231], v[208:211], v[44:47]
	ds_write_b128 v166, v[84:87] offset:20480
	v_mfma_f32_16x16x32_bf16 v[48:51], v[216:219], v[212:215], v[48:51]
	ds_write_b128 v166, v[72:75] offset:8192
	v_mfma_f32_16x16x32_bf16 v[52:55], v[220:223], v[212:215], v[52:55]
	ds_write_b128 v166, v[88:91] offset:24576
	v_mfma_f32_16x16x32_bf16 v[56:59], v[224:227], v[212:215], v[56:59]
	ds_write_b128 v166, v[76:79] offset:12288
	v_mfma_f32_16x16x32_bf16 v[60:63], v[228:231], v[212:215], v[60:63]
	s_waitcnt lgkmcnt(8)
	ds_write_b128 v166, v[92:95] offset:28672
	v_mfma_f32_16x16x32_bf16 v[0:3], v[138:141], v[232:235], v[0:3]
	v_mfma_f32_16x16x32_bf16 v[4:7], v[142:145], v[232:235], v[4:7]
	v_mfma_f32_16x16x32_bf16 v[8:11], v[146:149], v[232:235], v[8:11]
	v_mfma_f32_16x16x32_bf16 v[12:15], v[150:153], v[232:235], v[12:15]
	s_waitcnt lgkmcnt(8)
	v_mfma_f32_16x16x32_bf16 v[16:19], v[138:141], v[236:239], v[16:19]
	v_mfma_f32_16x16x32_bf16 v[20:23], v[142:145], v[236:239], v[20:23]
	v_mfma_f32_16x16x32_bf16 v[24:27], v[146:149], v[236:239], v[24:27]
	v_mfma_f32_16x16x32_bf16 v[28:31], v[150:153], v[236:239], v[28:31]
	v_mfma_f32_16x16x32_bf16 v[32:35], v[138:141], v[240:243], v[32:35]
	v_mfma_f32_16x16x32_bf16 v[36:39], v[142:145], v[240:243], v[36:39]
	v_mfma_f32_16x16x32_bf16 v[40:43], v[146:149], v[240:243], v[40:43]
	v_mfma_f32_16x16x32_bf16 v[44:47], v[150:153], v[240:243], v[44:47]
	v_mfma_f32_16x16x32_bf16 v[48:51], v[138:141], v[244:247], v[48:51]
	v_mfma_f32_16x16x32_bf16 v[52:55], v[142:145], v[244:247], v[52:55]
	v_mfma_f32_16x16x32_bf16 v[56:59], v[146:149], v[244:247], v[56:59]
	v_mfma_f32_16x16x32_bf16 v[60:63], v[150:153], v[244:247], v[60:63]
	s_setprio 0
	s_waitcnt lgkmcnt(0)
	s_barrier
	ds_read_b128 v[216:219], v132 offset:16384
	ds_read_b128 v[200:203], v133
	ds_read_b128 v[220:223], v132 offset:18432
	ds_read_b128 v[224:227], v132 offset:20480
	ds_read_b128 v[228:231], v132 offset:22528
	ds_read_b128 v[204:207], v133 offset:2048
	ds_read_b128 v[208:211], v133 offset:4096
	ds_read_b128 v[212:215], v133 offset:6144
	s_setprio 1
	s_waitcnt lgkmcnt(3)
	v_mfma_f32_16x16x32_bf16 v[0:3], v[216:219], v[200:203], v[0:3]
	ds_read_b128 v[138:141], v130 offset:16384
	v_mfma_f32_16x16x32_bf16 v[4:7], v[220:223], v[200:203], v[4:7]
	ds_read_b128 v[232:235], v131
	v_mfma_f32_16x16x32_bf16 v[8:11], v[224:227], v[200:203], v[8:11]
	ds_read_b128 v[142:145], v130 offset:18432
	v_mfma_f32_16x16x32_bf16 v[12:15], v[228:231], v[200:203], v[12:15]
	ds_read_b128 v[146:149], v130 offset:20480
	s_waitcnt lgkmcnt(4)
	v_mfma_f32_16x16x32_bf16 v[16:19], v[216:219], v[204:207], v[16:19]
	ds_read_b128 v[150:153], v130 offset:22528
	v_mfma_f32_16x16x32_bf16 v[20:23], v[220:223], v[204:207], v[20:23]
	ds_read_b128 v[236:239], v131 offset:2048
	v_mfma_f32_16x16x32_bf16 v[24:27], v[224:227], v[204:207], v[24:27]
	ds_read_b128 v[240:243], v131 offset:4096
	v_mfma_f32_16x16x32_bf16 v[28:31], v[228:231], v[204:207], v[28:31]
	ds_read_b128 v[244:247], v131 offset:6144
	v_mfma_f32_16x16x32_bf16 v[32:35], v[216:219], v[208:211], v[32:35]
	s_waitcnt vmcnt(0)
	ds_write_b128 v166, v[168:171] offset:32768
	v_mfma_f32_16x16x32_bf16 v[36:39], v[220:223], v[208:211], v[36:39]
	ds_write_b128 v166, v[184:187] offset:49152
	v_mfma_f32_16x16x32_bf16 v[40:43], v[224:227], v[208:211], v[40:43]
	ds_write_b128 v166, v[172:175] offset:36864
	v_mfma_f32_16x16x32_bf16 v[44:47], v[228:231], v[208:211], v[44:47]
	ds_write_b128 v166, v[188:191] offset:53248
	v_mfma_f32_16x16x32_bf16 v[48:51], v[216:219], v[212:215], v[48:51]
	ds_write_b128 v166, v[176:179] offset:40960
	v_mfma_f32_16x16x32_bf16 v[52:55], v[220:223], v[212:215], v[52:55]
	ds_write_b128 v166, v[192:195] offset:57344
	v_mfma_f32_16x16x32_bf16 v[56:59], v[224:227], v[212:215], v[56:59]
	ds_write_b128 v166, v[180:183] offset:45056
	v_mfma_f32_16x16x32_bf16 v[60:63], v[228:231], v[212:215], v[60:63]
	s_waitcnt lgkmcnt(8)
	ds_write_b128 v166, v[196:199] offset:61440
	v_mfma_f32_16x16x32_bf16 v[0:3], v[138:141], v[232:235], v[0:3]
	v_mfma_f32_16x16x32_bf16 v[4:7], v[142:145], v[232:235], v[4:7]
	v_mfma_f32_16x16x32_bf16 v[8:11], v[146:149], v[232:235], v[8:11]
	v_mfma_f32_16x16x32_bf16 v[12:15], v[150:153], v[232:235], v[12:15]
	s_waitcnt lgkmcnt(8)
	v_mfma_f32_16x16x32_bf16 v[16:19], v[138:141], v[236:239], v[16:19]
	v_mfma_f32_16x16x32_bf16 v[20:23], v[142:145], v[236:239], v[20:23]
	v_mfma_f32_16x16x32_bf16 v[24:27], v[146:149], v[236:239], v[24:27]
	v_mfma_f32_16x16x32_bf16 v[28:31], v[150:153], v[236:239], v[28:31]
	v_mfma_f32_16x16x32_bf16 v[32:35], v[138:141], v[240:243], v[32:35]
	v_mfma_f32_16x16x32_bf16 v[36:39], v[142:145], v[240:243], v[36:39]
	v_mfma_f32_16x16x32_bf16 v[40:43], v[146:149], v[240:243], v[40:43]
	v_mfma_f32_16x16x32_bf16 v[44:47], v[150:153], v[240:243], v[44:47]
	v_mfma_f32_16x16x32_bf16 v[48:51], v[138:141], v[244:247], v[48:51]
	v_mfma_f32_16x16x32_bf16 v[52:55], v[142:145], v[244:247], v[52:55]
	v_mfma_f32_16x16x32_bf16 v[56:59], v[146:149], v[244:247], v[56:59]
	v_mfma_f32_16x16x32_bf16 v[60:63], v[150:153], v[244:247], v[60:63]
	s_setprio 0
	s_waitcnt lgkmcnt(0)
	s_barrier
	ds_read_b128 v[216:219], v132 offset:49152
	ds_read_b128 v[200:203], v133 offset:32768
	ds_read_b128 v[220:223], v132 offset:51200
	ds_read_b128 v[224:227], v132 offset:53248
	ds_read_b128 v[228:231], v132 offset:55296
	ds_read_b128 v[204:207], v133 offset:34816
	ds_read_b128 v[208:211], v133 offset:36864
	ds_read_b128 v[212:215], v133 offset:38912
	s_setprio 1
	s_waitcnt lgkmcnt(3)
	v_mfma_f32_16x16x32_bf16 v[0:3], v[216:219], v[200:203], v[0:3]
	ds_read_b128 v[138:141], v130 offset:49152
	v_mfma_f32_16x16x32_bf16 v[4:7], v[220:223], v[200:203], v[4:7]
	ds_read_b128 v[232:235], v131 offset:32768
	v_mfma_f32_16x16x32_bf16 v[8:11], v[224:227], v[200:203], v[8:11]
	ds_read_b128 v[142:145], v130 offset:51200
	v_mfma_f32_16x16x32_bf16 v[12:15], v[228:231], v[200:203], v[12:15]
	ds_read_b128 v[146:149], v130 offset:53248
	s_waitcnt lgkmcnt(4)
	v_mfma_f32_16x16x32_bf16 v[16:19], v[216:219], v[204:207], v[16:19]
	ds_read_b128 v[150:153], v130 offset:55296
	v_mfma_f32_16x16x32_bf16 v[20:23], v[220:223], v[204:207], v[20:23]
	ds_read_b128 v[236:239], v131 offset:34816
	v_mfma_f32_16x16x32_bf16 v[24:27], v[224:227], v[204:207], v[24:27]
	ds_read_b128 v[240:243], v131 offset:36864
	v_mfma_f32_16x16x32_bf16 v[28:31], v[228:231], v[204:207], v[28:31]
	ds_read_b128 v[244:247], v131 offset:38912
	v_mfma_f32_16x16x32_bf16 v[32:35], v[216:219], v[208:211], v[32:35]
	v_mfma_f32_16x16x32_bf16 v[36:39], v[220:223], v[208:211], v[36:39]
	v_mfma_f32_16x16x32_bf16 v[40:43], v[224:227], v[208:211], v[40:43]
	v_mfma_f32_16x16x32_bf16 v[44:47], v[228:231], v[208:211], v[44:47]
	v_mfma_f32_16x16x32_bf16 v[48:51], v[216:219], v[212:215], v[48:51]
	v_mfma_f32_16x16x32_bf16 v[52:55], v[220:223], v[212:215], v[52:55]
	v_mfma_f32_16x16x32_bf16 v[56:59], v[224:227], v[212:215], v[56:59]
	v_mfma_f32_16x16x32_bf16 v[60:63], v[228:231], v[212:215], v[60:63]
	s_waitcnt lgkmcnt(3)
	v_mfma_f32_16x16x32_bf16 v[0:3], v[138:141], v[232:235], v[0:3]
	v_mfma_f32_16x16x32_bf16 v[4:7], v[142:145], v[232:235], v[4:7]
	v_mfma_f32_16x16x32_bf16 v[8:11], v[146:149], v[232:235], v[8:11]
	v_mfma_f32_16x16x32_bf16 v[12:15], v[150:153], v[232:235], v[12:15]
	s_waitcnt lgkmcnt(0)
	v_mfma_f32_16x16x32_bf16 v[16:19], v[138:141], v[236:239], v[16:19]
	v_mfma_f32_16x16x32_bf16 v[20:23], v[142:145], v[236:239], v[20:23]
	v_mfma_f32_16x16x32_bf16 v[24:27], v[146:149], v[236:239], v[24:27]
	v_mfma_f32_16x16x32_bf16 v[28:31], v[150:153], v[236:239], v[28:31]
	v_mfma_f32_16x16x32_bf16 v[32:35], v[138:141], v[240:243], v[32:35]
	v_mfma_f32_16x16x32_bf16 v[36:39], v[142:145], v[240:243], v[36:39]
	v_mfma_f32_16x16x32_bf16 v[40:43], v[146:149], v[240:243], v[40:43]
	v_mfma_f32_16x16x32_bf16 v[44:47], v[150:153], v[240:243], v[44:47]
	v_mfma_f32_16x16x32_bf16 v[48:51], v[138:141], v[244:247], v[48:51]
	v_mfma_f32_16x16x32_bf16 v[52:55], v[142:145], v[244:247], v[52:55]
	v_mfma_f32_16x16x32_bf16 v[56:59], v[146:149], v[244:247], v[56:59]
	v_mfma_f32_16x16x32_bf16 v[60:63], v[150:153], v[244:247], v[60:63]
	s_setprio 0
	s_nop 7
	s_barrier
	ds_write_b128 v136, v[0:3]
	ds_write_b128 v136, v[4:7] offset:64
	ds_write_b128 v136, v[8:11] offset:128
	ds_write_b128 v136, v[12:15] offset:192
	ds_write_b128 v136, v[16:19] offset:8448
	ds_write_b128 v136, v[20:23] offset:8512
	ds_write_b128 v136, v[24:27] offset:8576
	ds_write_b128 v136, v[28:31] offset:8640
	ds_write_b128 v136, v[32:35] offset:16896
	ds_write_b128 v136, v[36:39] offset:16960
	ds_write_b128 v136, v[40:43] offset:17024
	ds_write_b128 v136, v[44:47] offset:17088
	ds_write_b128 v136, v[48:51] offset:25344
	ds_write_b128 v136, v[52:55] offset:25408
	ds_write_b128 v136, v[56:59] offset:25472
	ds_write_b128 v136, v[60:63] offset:25536
	v_lshl_or_b32 v20, s62, 6, v107
	v_ashrrev_i32_e32 v21, 31, v20
	v_lshlrev_b64 v[22:23], 2, v[20:21]
	v_lshl_add_u64 v[0:1], s[82:83], 0, v[22:23]
	v_lshl_add_u64 v[16:17], s[28:29], 0, v[22:23]
	v_lshl_add_u64 v[18:19], s[30:31], 0, v[22:23]
	s_waitcnt lgkmcnt(0)
	s_barrier
	v_lshl_add_u64 v[2:3], s[18:19], 0, v[22:23]
	v_lshl_add_u64 v[4:5], s[22:23], 0, v[22:23]
	v_lshl_add_u64 v[6:7], s[26:27], 0, v[22:23]
	global_load_dwordx2 v[8:9], v[0:1], off
	global_load_dwordx2 v[10:11], v[2:3], off
	global_load_dwordx2 v[12:13], v[4:5], off
	global_load_dwordx2 v[14:15], v[6:7], off
	s_nop 0
	global_load_dwordx2 v[16:17], v[16:17], off
	s_nop 0
	global_load_dwordx2 v[18:19], v[18:19], off
	s_mov_b64 s[4:5], -1
	s_and_b64 vcc, exec, s[36:37]
	s_cbranch_vccz .LBB0_852
	s_mul_i32 s65, s34, 17
	s_sub_i32 s64, s61, s65
	s_cmp_lt_i32 s64, 1
	s_cbranch_scc1 .Lp7epi_slow
	s_cmp_gt_i32 s64, 15
	s_cbranch_scc1 .Lp7epi_slow
	v_add_u32_e32 v127, 0x840, v134
	v_add_u32_e32 v128, 0x1080, v134
	v_add_u32_e32 v129, 0x18c0, v134
	s_mov_b64 s[70:71], exec
	s_and_b64 exec, exec, s[0:1]
	ds_read2_b64 v[232:235], v111 offset1:16
	ds_read2_b64 v[236:239], v113 offset1:16
	s_mov_b64 exec, s[70:71]
	ds_read2_b64 v[168:171], v134 offset0:0 offset1:16
	ds_read2_b64 v[172:175], v134 offset0:66 offset1:82
	ds_read2_b64 v[176:179], v134 offset0:132 offset1:148
	ds_read2_b64 v[180:183], v134 offset0:198 offset1:214
	ds_read2_b64 v[184:187], v127 offset0:0 offset1:16
	ds_read2_b64 v[188:191], v127 offset0:66 offset1:82
	ds_read2_b64 v[192:195], v127 offset0:132 offset1:148
	ds_read2_b64 v[196:199], v127 offset0:198 offset1:214
	ds_read2_b64 v[200:203], v128 offset0:0 offset1:16
	ds_read2_b64 v[204:207], v128 offset0:66 offset1:82
	ds_read2_b64 v[208:211], v128 offset0:132 offset1:148
	ds_read2_b64 v[212:215], v128 offset0:198 offset1:214
	ds_read2_b64 v[216:219], v129 offset0:0 offset1:16
	s_waitcnt lgkmcnt(8)
	ds_read2_b64 v[220:223], v129 offset0:66 offset1:82
	ds_read2_b64 v[224:227], v129 offset0:132 offset1:148
	ds_read2_b64 v[228:231], v129 offset0:198 offset1:214
	s_lshl_b32 s65, s34, 11
	s_mul_i32 s72, s64, 0x7e
	s_add_i32 s65, s65, s72
	s_add_i32 s65, s65, -2
	s_mul_i32 s65, s65, 0x1600
	s_add_u32 s66, s80, s65
	s_addc_u32 s67, s81, 0
	v_mul_u32_u24_e32 v126, 0x1600, v105
	v_lshl_add_u32 v126, v20, 1, v126
	s_waitcnt vmcnt(0)
	v_mul_f32_e32 v40, v8, v232
	v_mul_f32_e32 v48, v8, v236
	v_mul_f32_e32 v56, v8, v168
	v_mul_f32_e32 v64, v8, v172
	v_mul_f32_e32 v41, v9, v233
	v_mul_f32_e32 v49, v9, v237
	v_mul_f32_e32 v57, v9, v169
	v_mul_f32_e32 v65, v9, v173
	v_mul_f32_e32 v42, v14, v234
	v_mul_f32_e32 v50, v14, v238
	v_mul_f32_e32 v58, v14, v170
	v_mul_f32_e32 v66, v14, v174
	v_mul_f32_e32 v43, v15, v235
	v_mul_f32_e32 v51, v15, v239
	v_mul_f32_e32 v59, v15, v171
	v_mul_f32_e32 v67, v15, v175
	v_fma_f32 v40, v10, v236, v40
	v_fma_f32 v48, v10, v168, v48
	v_fma_f32 v56, v10, v172, v56
	v_fma_f32 v64, v10, v176, v64
	v_fma_f32 v41, v11, v237, v41
	v_fma_f32 v49, v11, v169, v49
	v_fma_f32 v57, v11, v173, v57
	v_fma_f32 v65, v11, v177, v65
	v_fma_f32 v42, v16, v238, v42
	v_fma_f32 v50, v16, v170, v50
	v_fma_f32 v58, v16, v174, v58
	v_fma_f32 v66, v16, v178, v66
	v_fma_f32 v43, v17, v239, v43
	v_fma_f32 v51, v17, v171, v51
	v_fma_f32 v59, v17, v175, v59
	v_fma_f32 v67, v17, v179, v67
	v_fma_f32 v40, v12, v168, v40
	v_fma_f32 v48, v12, v172, v48
	v_fma_f32 v56, v12, v176, v56
	v_fma_f32 v64, v12, v180, v64
	v_fma_f32 v41, v13, v169, v41
	v_fma_f32 v49, v13, v173, v49
	v_fma_f32 v57, v13, v177, v57
	v_fma_f32 v65, v13, v181, v65
	v_fma_f32 v42, v18, v170, v42
	v_fma_f32 v50, v18, v174, v50
	v_fma_f32 v58, v18, v178, v58
	v_fma_f32 v66, v18, v182, v66
	v_fma_f32 v43, v19, v171, v43
	v_fma_f32 v51, v19, v175, v51
	v_fma_f32 v59, v19, v179, v59
	v_fma_f32 v67, v19, v183, v67
	v_mul_f32_e32 v44, 0xbfb8aa3b, v40
	v_mul_f32_e32 v52, 0xbfb8aa3b, v48
	v_mul_f32_e32 v60, 0xbfb8aa3b, v56
	v_mul_f32_e32 v68, 0xbfb8aa3b, v64
	v_mul_f32_e32 v45, 0xbfb8aa3b, v41
	v_mul_f32_e32 v53, 0xbfb8aa3b, v49
	v_mul_f32_e32 v61, 0xbfb8aa3b, v57
	v_mul_f32_e32 v69, 0xbfb8aa3b, v65
	v_exp_f32_e32 v44, v44
	v_exp_f32_e32 v52, v52
	v_exp_f32_e32 v60, v60
	v_exp_f32_e32 v68, v68
	v_exp_f32_e32 v45, v45
	v_exp_f32_e32 v53, v53
	v_exp_f32_e32 v61, v61
	v_exp_f32_e32 v69, v69
	v_add_f32_e32 v44, 1.0, v44
	v_add_f32_e32 v52, 1.0, v52
	v_add_f32_e32 v60, 1.0, v60
	v_add_f32_e32 v68, 1.0, v68
	v_add_f32_e32 v45, 1.0, v45
	v_add_f32_e32 v53, 1.0, v53
	v_add_f32_e32 v61, 1.0, v61
	v_add_f32_e32 v69, 1.0, v69
	v_rcp_f32_e32 v44, v44
	v_rcp_f32_e32 v52, v52
	v_rcp_f32_e32 v60, v60
	v_rcp_f32_e32 v68, v68
	v_rcp_f32_e32 v45, v45
	v_rcp_f32_e32 v53, v53
	v_rcp_f32_e32 v61, v61
	v_rcp_f32_e32 v69, v69
	v_mul_f32_e32 v40, v40, v44
	v_mul_f32_e32 v48, v48, v52
	v_mul_f32_e32 v56, v56, v60
	v_mul_f32_e32 v64, v64, v68
	v_mul_f32_e32 v41, v41, v45
	v_mul_f32_e32 v49, v49, v53
	v_mul_f32_e32 v57, v57, v61
	v_mul_f32_e32 v65, v65, v69
	v_mul_f32_e32 v40, v42, v40
	v_mul_f32_e32 v48, v50, v48
	v_mul_f32_e32 v56, v58, v56
	v_mul_f32_e32 v64, v66, v64
	v_mul_f32_e32 v41, v43, v41
	v_mul_f32_e32 v49, v51, v49
	v_mul_f32_e32 v57, v59, v57
	v_mul_f32_e32 v65, v67, v65
	v_cvt_pk_bf16_f32 v80, v40, v41
	v_cvt_pk_bf16_f32 v81, v48, v49
	v_cvt_pk_bf16_f32 v82, v56, v57
	v_cvt_pk_bf16_f32 v83, v64, v65
	s_waitcnt lgkmcnt(10)
	s_waitcnt lgkmcnt(9)
	s_waitcnt lgkmcnt(8)
	v_mul_f32_e32 v40, v8, v176
	v_mul_f32_e32 v48, v8, v180
	v_mul_f32_e32 v56, v8, v184
	v_mul_f32_e32 v64, v8, v188
	v_mul_f32_e32 v41, v9, v177
	v_mul_f32_e32 v49, v9, v181
	v_mul_f32_e32 v57, v9, v185
	v_mul_f32_e32 v65, v9, v189
	v_mul_f32_e32 v42, v14, v178
	v_mul_f32_e32 v50, v14, v182
	v_mul_f32_e32 v58, v14, v186
	v_mul_f32_e32 v66, v14, v190
	v_mul_f32_e32 v43, v15, v179
	v_mul_f32_e32 v51, v15, v183
	v_mul_f32_e32 v59, v15, v187
	v_mul_f32_e32 v67, v15, v191
	v_fma_f32 v40, v10, v180, v40
	v_fma_f32 v48, v10, v184, v48
	v_fma_f32 v56, v10, v188, v56
	v_fma_f32 v64, v10, v192, v64
	v_fma_f32 v41, v11, v181, v41
	v_fma_f32 v49, v11, v185, v49
	v_fma_f32 v57, v11, v189, v57
	v_fma_f32 v65, v11, v193, v65
	v_fma_f32 v42, v16, v182, v42
	v_fma_f32 v50, v16, v186, v50
	v_fma_f32 v58, v16, v190, v58
	v_fma_f32 v66, v16, v194, v66
	v_fma_f32 v43, v17, v183, v43
	v_fma_f32 v51, v17, v187, v51
	v_fma_f32 v59, v17, v191, v59
	v_fma_f32 v67, v17, v195, v67
	v_fma_f32 v40, v12, v184, v40
	v_fma_f32 v48, v12, v188, v48
	v_fma_f32 v56, v12, v192, v56
	v_fma_f32 v64, v12, v196, v64
	v_fma_f32 v41, v13, v185, v41
	v_fma_f32 v49, v13, v189, v49
	v_fma_f32 v57, v13, v193, v57
	v_fma_f32 v65, v13, v197, v65
	v_fma_f32 v42, v18, v186, v42
	v_fma_f32 v50, v18, v190, v50
	v_fma_f32 v58, v18, v194, v58
	v_fma_f32 v66, v18, v198, v66
	v_fma_f32 v43, v19, v187, v43
	v_fma_f32 v51, v19, v191, v51
	v_fma_f32 v59, v19, v195, v59
	v_fma_f32 v67, v19, v199, v67
	v_mul_f32_e32 v44, 0xbfb8aa3b, v40
	v_mul_f32_e32 v52, 0xbfb8aa3b, v48
	v_mul_f32_e32 v60, 0xbfb8aa3b, v56
	v_mul_f32_e32 v68, 0xbfb8aa3b, v64
	v_mul_f32_e32 v45, 0xbfb8aa3b, v41
	v_mul_f32_e32 v53, 0xbfb8aa3b, v49
	v_mul_f32_e32 v61, 0xbfb8aa3b, v57
	v_mul_f32_e32 v69, 0xbfb8aa3b, v65
	v_exp_f32_e32 v44, v44
	v_exp_f32_e32 v52, v52
	v_exp_f32_e32 v60, v60
	v_exp_f32_e32 v68, v68
	v_exp_f32_e32 v45, v45
	v_exp_f32_e32 v53, v53
	v_exp_f32_e32 v61, v61
	v_exp_f32_e32 v69, v69
	v_add_f32_e32 v44, 1.0, v44
	v_add_f32_e32 v52, 1.0, v52
	v_add_f32_e32 v60, 1.0, v60
	v_add_f32_e32 v68, 1.0, v68
	v_add_f32_e32 v45, 1.0, v45
	v_add_f32_e32 v53, 1.0, v53
	v_add_f32_e32 v61, 1.0, v61
	v_add_f32_e32 v69, 1.0, v69
	v_rcp_f32_e32 v44, v44
	v_rcp_f32_e32 v52, v52
	v_rcp_f32_e32 v60, v60
	v_rcp_f32_e32 v68, v68
	v_rcp_f32_e32 v45, v45
	v_rcp_f32_e32 v53, v53
	v_rcp_f32_e32 v61, v61
	v_rcp_f32_e32 v69, v69
	v_mul_f32_e32 v40, v40, v44
	v_mul_f32_e32 v48, v48, v52
	v_mul_f32_e32 v56, v56, v60
	v_mul_f32_e32 v64, v64, v68
	v_mul_f32_e32 v41, v41, v45
	v_mul_f32_e32 v49, v49, v53
	v_mul_f32_e32 v57, v57, v61
	v_mul_f32_e32 v65, v65, v69
	v_mul_f32_e32 v40, v42, v40
	v_mul_f32_e32 v48, v50, v48
	v_mul_f32_e32 v56, v58, v56
	v_mul_f32_e32 v64, v66, v64
	v_mul_f32_e32 v41, v43, v41
	v_mul_f32_e32 v49, v51, v49
	v_mul_f32_e32 v57, v59, v57
	v_mul_f32_e32 v65, v67, v65
	v_cvt_pk_bf16_f32 v84, v40, v41
	v_cvt_pk_bf16_f32 v85, v48, v49
	v_cvt_pk_bf16_f32 v86, v56, v57
	v_cvt_pk_bf16_f32 v87, v64, v65
	s_waitcnt lgkmcnt(7)
	s_waitcnt lgkmcnt(6)
	s_waitcnt lgkmcnt(5)
	s_waitcnt lgkmcnt(4)
	v_mul_f32_e32 v40, v8, v192
	v_mul_f32_e32 v48, v8, v196
	v_mul_f32_e32 v56, v8, v200
	v_mul_f32_e32 v64, v8, v204
	v_mul_f32_e32 v41, v9, v193
	v_mul_f32_e32 v49, v9, v197
	v_mul_f32_e32 v57, v9, v201
	v_mul_f32_e32 v65, v9, v205
	v_mul_f32_e32 v42, v14, v194
	v_mul_f32_e32 v50, v14, v198
	v_mul_f32_e32 v58, v14, v202
	v_mul_f32_e32 v66, v14, v206
	v_mul_f32_e32 v43, v15, v195
	v_mul_f32_e32 v51, v15, v199
	v_mul_f32_e32 v59, v15, v203
	v_mul_f32_e32 v67, v15, v207
	v_fma_f32 v40, v10, v196, v40
	v_fma_f32 v48, v10, v200, v48
	v_fma_f32 v56, v10, v204, v56
	v_fma_f32 v64, v10, v208, v64
	v_fma_f32 v41, v11, v197, v41
	v_fma_f32 v49, v11, v201, v49
	v_fma_f32 v57, v11, v205, v57
	v_fma_f32 v65, v11, v209, v65
	v_fma_f32 v42, v16, v198, v42
	v_fma_f32 v50, v16, v202, v50
	v_fma_f32 v58, v16, v206, v58
	v_fma_f32 v66, v16, v210, v66
	v_fma_f32 v43, v17, v199, v43
	v_fma_f32 v51, v17, v203, v51
	v_fma_f32 v59, v17, v207, v59
	v_fma_f32 v67, v17, v211, v67
	v_fma_f32 v40, v12, v200, v40
	v_fma_f32 v48, v12, v204, v48
	v_fma_f32 v56, v12, v208, v56
	v_fma_f32 v64, v12, v212, v64
	v_fma_f32 v41, v13, v201, v41
	v_fma_f32 v49, v13, v205, v49
	v_fma_f32 v57, v13, v209, v57
	v_fma_f32 v65, v13, v213, v65
	v_fma_f32 v42, v18, v202, v42
	v_fma_f32 v50, v18, v206, v50
	v_fma_f32 v58, v18, v210, v58
	v_fma_f32 v66, v18, v214, v66
	v_fma_f32 v43, v19, v203, v43
	v_fma_f32 v51, v19, v207, v51
	v_fma_f32 v59, v19, v211, v59
	v_fma_f32 v67, v19, v215, v67
	v_mul_f32_e32 v44, 0xbfb8aa3b, v40
	v_mul_f32_e32 v52, 0xbfb8aa3b, v48
	v_mul_f32_e32 v60, 0xbfb8aa3b, v56
	v_mul_f32_e32 v68, 0xbfb8aa3b, v64
	v_mul_f32_e32 v45, 0xbfb8aa3b, v41
	v_mul_f32_e32 v53, 0xbfb8aa3b, v49
	v_mul_f32_e32 v61, 0xbfb8aa3b, v57
	v_mul_f32_e32 v69, 0xbfb8aa3b, v65
	v_exp_f32_e32 v44, v44
	v_exp_f32_e32 v52, v52
	v_exp_f32_e32 v60, v60
	v_exp_f32_e32 v68, v68
	v_exp_f32_e32 v45, v45
	v_exp_f32_e32 v53, v53
	v_exp_f32_e32 v61, v61
	v_exp_f32_e32 v69, v69
	v_add_f32_e32 v44, 1.0, v44
	v_add_f32_e32 v52, 1.0, v52
	v_add_f32_e32 v60, 1.0, v60
	v_add_f32_e32 v68, 1.0, v68
	v_add_f32_e32 v45, 1.0, v45
	v_add_f32_e32 v53, 1.0, v53
	v_add_f32_e32 v61, 1.0, v61
	v_add_f32_e32 v69, 1.0, v69
	v_rcp_f32_e32 v44, v44
	v_rcp_f32_e32 v52, v52
	v_rcp_f32_e32 v60, v60
	v_rcp_f32_e32 v68, v68
	v_rcp_f32_e32 v45, v45
	v_rcp_f32_e32 v53, v53
	v_rcp_f32_e32 v61, v61
	v_rcp_f32_e32 v69, v69
	v_mul_f32_e32 v40, v40, v44
	v_mul_f32_e32 v48, v48, v52
	v_mul_f32_e32 v56, v56, v60
	v_mul_f32_e32 v64, v64, v68
	v_mul_f32_e32 v41, v41, v45
	v_mul_f32_e32 v49, v49, v53
	v_mul_f32_e32 v57, v57, v61
	v_mul_f32_e32 v65, v65, v69
	v_mul_f32_e32 v40, v42, v40
	v_mul_f32_e32 v48, v50, v48
	v_mul_f32_e32 v56, v58, v56
	v_mul_f32_e32 v64, v66, v64
	v_mul_f32_e32 v41, v43, v41
	v_mul_f32_e32 v49, v51, v49
	v_mul_f32_e32 v57, v59, v57
	v_mul_f32_e32 v65, v67, v65
	v_cvt_pk_bf16_f32 v88, v40, v41
	v_cvt_pk_bf16_f32 v89, v48, v49
	v_cvt_pk_bf16_f32 v90, v56, v57
	v_cvt_pk_bf16_f32 v91, v64, v65
	s_waitcnt lgkmcnt(3)
	s_waitcnt lgkmcnt(2)
	s_waitcnt lgkmcnt(1)
	s_waitcnt lgkmcnt(0)
	v_mul_f32_e32 v40, v8, v208
	v_mul_f32_e32 v48, v8, v212
	v_mul_f32_e32 v56, v8, v216
	v_mul_f32_e32 v64, v8, v220
	v_mul_f32_e32 v41, v9, v209
	v_mul_f32_e32 v49, v9, v213
	v_mul_f32_e32 v57, v9, v217
	v_mul_f32_e32 v65, v9, v221
	v_mul_f32_e32 v42, v14, v210
	v_mul_f32_e32 v50, v14, v214
	v_mul_f32_e32 v58, v14, v218
	v_mul_f32_e32 v66, v14, v222
	v_mul_f32_e32 v43, v15, v211
	v_mul_f32_e32 v51, v15, v215
	v_mul_f32_e32 v59, v15, v219
	v_mul_f32_e32 v67, v15, v223
	v_fma_f32 v40, v10, v212, v40
	v_fma_f32 v48, v10, v216, v48
	v_fma_f32 v56, v10, v220, v56
	v_fma_f32 v64, v10, v224, v64
	v_fma_f32 v41, v11, v213, v41
	v_fma_f32 v49, v11, v217, v49
	v_fma_f32 v57, v11, v221, v57
	v_fma_f32 v65, v11, v225, v65
	v_fma_f32 v42, v16, v214, v42
	v_fma_f32 v50, v16, v218, v50
	v_fma_f32 v58, v16, v222, v58
	v_fma_f32 v66, v16, v226, v66
	v_fma_f32 v43, v17, v215, v43
	v_fma_f32 v51, v17, v219, v51
	v_fma_f32 v59, v17, v223, v59
	v_fma_f32 v67, v17, v227, v67
	v_fma_f32 v40, v12, v216, v40
	v_fma_f32 v48, v12, v220, v48
	v_fma_f32 v56, v12, v224, v56
	v_fma_f32 v64, v12, v228, v64
	v_fma_f32 v41, v13, v217, v41
	v_fma_f32 v49, v13, v221, v49
	v_fma_f32 v57, v13, v225, v57
	v_fma_f32 v65, v13, v229, v65
	v_fma_f32 v42, v18, v218, v42
	v_fma_f32 v50, v18, v222, v50
	v_fma_f32 v58, v18, v226, v58
	v_fma_f32 v66, v18, v230, v66
	v_fma_f32 v43, v19, v219, v43
	v_fma_f32 v51, v19, v223, v51
	v_fma_f32 v59, v19, v227, v59
	v_fma_f32 v67, v19, v231, v67
	v_mul_f32_e32 v44, 0xbfb8aa3b, v40
	v_mul_f32_e32 v52, 0xbfb8aa3b, v48
	v_mul_f32_e32 v60, 0xbfb8aa3b, v56
	v_mul_f32_e32 v68, 0xbfb8aa3b, v64
	v_mul_f32_e32 v45, 0xbfb8aa3b, v41
	v_mul_f32_e32 v53, 0xbfb8aa3b, v49
	v_mul_f32_e32 v61, 0xbfb8aa3b, v57
	v_mul_f32_e32 v69, 0xbfb8aa3b, v65
	v_exp_f32_e32 v44, v44
	v_exp_f32_e32 v52, v52
	v_exp_f32_e32 v60, v60
	v_exp_f32_e32 v68, v68
	v_exp_f32_e32 v45, v45
	v_exp_f32_e32 v53, v53
	v_exp_f32_e32 v61, v61
	v_exp_f32_e32 v69, v69
	v_add_f32_e32 v44, 1.0, v44
	v_add_f32_e32 v52, 1.0, v52
	v_add_f32_e32 v60, 1.0, v60
	v_add_f32_e32 v68, 1.0, v68
	v_add_f32_e32 v45, 1.0, v45
	v_add_f32_e32 v53, 1.0, v53
	v_add_f32_e32 v61, 1.0, v61
	v_add_f32_e32 v69, 1.0, v69
	v_rcp_f32_e32 v44, v44
	v_rcp_f32_e32 v52, v52
	v_rcp_f32_e32 v60, v60
	v_rcp_f32_e32 v68, v68
	v_rcp_f32_e32 v45, v45
	v_rcp_f32_e32 v53, v53
	v_rcp_f32_e32 v61, v61
	v_rcp_f32_e32 v69, v69
	v_mul_f32_e32 v40, v40, v44
	v_mul_f32_e32 v48, v48, v52
	v_mul_f32_e32 v56, v56, v60
	v_mul_f32_e32 v64, v64, v68
	v_mul_f32_e32 v41, v41, v45
	v_mul_f32_e32 v49, v49, v53
	v_mul_f32_e32 v57, v57, v61
	v_mul_f32_e32 v65, v65, v69
	v_mul_f32_e32 v40, v42, v40
	v_mul_f32_e32 v48, v50, v48
	v_mul_f32_e32 v56, v58, v56
	v_mul_f32_e32 v64, v66, v64
	v_mul_f32_e32 v41, v43, v41
	v_mul_f32_e32 v49, v51, v49
	v_mul_f32_e32 v57, v59, v57
	v_mul_f32_e32 v65, v67, v65
	v_cvt_pk_bf16_f32 v92, v40, v41
	v_cvt_pk_bf16_f32 v93, v48, v49
	v_cvt_pk_bf16_f32 v94, v56, v57
	v_cvt_pk_bf16_f32 v95, v64, v65
	s_and_b64 exec, exec, s[0:1]
	global_store_dword v126, v80, s[66:67]
	s_add_u32 s66, s66, 0x1600
	s_addc_u32 s67, s67, 0
	global_store_dword v126, v81, s[66:67]
	s_add_u32 s66, s66, 0x1600
	s_addc_u32 s67, s67, 0
	s_mov_b64 exec, s[70:71]
	global_store_dword v126, v82, s[66:67]
	s_add_u32 s66, s66, 0x1600
	s_addc_u32 s67, s67, 0
	global_store_dword v126, v83, s[66:67]
	s_add_u32 s66, s66, 0x1600
	s_addc_u32 s67, s67, 0
	global_store_dword v126, v84, s[66:67]
	s_add_u32 s66, s66, 0x1600
	s_addc_u32 s67, s67, 0
	global_store_dword v126, v85, s[66:67]
	s_add_u32 s66, s66, 0x1600
	s_addc_u32 s67, s67, 0
	global_store_dword v126, v86, s[66:67]
	s_add_u32 s66, s66, 0x1600
	s_addc_u32 s67, s67, 0
	global_store_dword v126, v87, s[66:67]
	s_add_u32 s66, s66, 0x1600
	s_addc_u32 s67, s67, 0
	global_store_dword v126, v88, s[66:67]
	s_add_u32 s66, s66, 0x1600
	s_addc_u32 s67, s67, 0
	global_store_dword v126, v89, s[66:67]
	s_add_u32 s66, s66, 0x1600
	s_addc_u32 s67, s67, 0
	global_store_dword v126, v90, s[66:67]
	s_add_u32 s66, s66, 0x1600
	s_addc_u32 s67, s67, 0
	global_store_dword v126, v91, s[66:67]
	s_add_u32 s66, s66, 0x1600
	s_addc_u32 s67, s67, 0
	global_store_dword v126, v92, s[66:67]
	s_add_u32 s66, s66, 0x1600
	s_addc_u32 s67, s67, 0
	global_store_dword v126, v93, s[66:67]
	s_add_u32 s66, s66, 0x1600
	s_addc_u32 s67, s67, 0
	global_store_dword v126, v94, s[66:67]
	s_add_u32 s66, s66, 0x1600
	s_addc_u32 s67, s67, 0
	global_store_dword v126, v95, s[66:67]
	s_branch .LBB0_851

.Lgm_p8_loop:
	ds_read_b128 v[184:187], v132 offset:16384
	ds_read_b128 v[168:171], v133
	ds_read_b128 v[188:191], v132 offset:18432
	ds_read_b128 v[192:195], v132 offset:20480
	ds_read_b128 v[196:199], v132 offset:22528
	ds_read_b128 v[172:175], v133 offset:2048
	ds_read_b128 v[176:179], v133 offset:4096
	ds_read_b128 v[180:183], v133 offset:6144
	ds_read_b128 v[200:203], v130 offset:16384
	ds_read_b128 v[204:207], v130 offset:18432
	ds_read_b128 v[208:211], v130 offset:20480
	ds_read_b128 v[212:215], v130 offset:22528
	s_setprio 1
	s_waitcnt lgkmcnt(7)
	v_mfma_f32_16x16x32_bf16 v[92:95], v[184:187], v[168:171], v[92:95]
	v_mfma_f32_16x16x32_bf16 v[88:91], v[188:191], v[168:171], v[88:91]
	v_mfma_f32_16x16x32_bf16 v[84:87], v[192:195], v[168:171], v[84:87]
	v_mfma_f32_16x16x32_bf16 v[146:149], v[196:199], v[168:171], v[146:149]
	ds_read_b128 v[168:171], v131
	s_waitcnt lgkmcnt(5)
	v_mfma_f32_16x16x32_bf16 v[44:47], v[184:187], v[172:175], v[44:47]
	s_waitcnt vmcnt(8)
	ds_write_b128 v166, v[80:83] offset:32768
	v_mfma_f32_16x16x32_bf16 v[40:43], v[188:191], v[172:175], v[40:43]
	ds_write_b128 v166, v[134:137] offset:49152
	v_mfma_f32_16x16x32_bf16 v[36:39], v[192:195], v[172:175], v[36:39]
	ds_write_b128 v166, v[116:119] offset:36864
	v_mfma_f32_16x16x32_bf16 v[32:35], v[196:199], v[172:175], v[32:35]
	ds_read_b128 v[172:175], v131 offset:2048
	v_mfma_f32_16x16x32_bf16 v[28:31], v[184:187], v[176:179], v[28:31]
	ds_write_b128 v166, v[138:141] offset:53248
	v_mfma_f32_16x16x32_bf16 v[24:27], v[188:191], v[176:179], v[24:27]
	ds_write_b128 v166, v[120:123] offset:40960
	v_mfma_f32_16x16x32_bf16 v[20:23], v[192:195], v[176:179], v[20:23]
	ds_write_b128 v166, v[142:145] offset:57344
	v_mfma_f32_16x16x32_bf16 v[16:19], v[196:199], v[176:179], v[16:19]
	ds_read_b128 v[176:179], v131 offset:4096
	v_mfma_f32_16x16x32_bf16 v[12:15], v[184:187], v[180:183], v[12:15]
	ds_write_b128 v166, v[124:127] offset:45056
	v_mfma_f32_16x16x32_bf16 v[8:11], v[188:191], v[180:183], v[8:11]
	ds_write_b128 v166, v[150:153] offset:61440
	v_mfma_f32_16x16x32_bf16 v[4:7], v[192:195], v[180:183], v[4:7]
	v_mfma_f32_16x16x32_bf16 v[0:3], v[196:199], v[180:183], v[0:3]
	s_waitcnt lgkmcnt(8)
	ds_read_b128 v[180:183], v131 offset:6144
	v_mfma_f32_16x16x32_bf16 v[92:95], v[200:203], v[168:171], v[92:95]
	v_mfma_f32_16x16x32_bf16 v[88:91], v[204:207], v[168:171], v[88:91]
	v_mfma_f32_16x16x32_bf16 v[84:87], v[208:211], v[168:171], v[84:87]
	v_mfma_f32_16x16x32_bf16 v[146:149], v[212:215], v[168:171], v[146:149]
	s_waitcnt lgkmcnt(0)
	v_mfma_f32_16x16x32_bf16 v[44:47], v[200:203], v[172:175], v[44:47]
	global_load_dwordx4 v[80:83], v102, s[100:101] offset:384
	v_mfma_f32_16x16x32_bf16 v[40:43], v[204:207], v[172:175], v[40:43]
	global_load_dwordx4 v[134:137], v114, s[98:99] offset:384
	v_mfma_f32_16x16x32_bf16 v[36:39], v[208:211], v[172:175], v[36:39]
	global_load_dwordx4 v[116:119], v103, s[100:101] offset:384
	v_mfma_f32_16x16x32_bf16 v[32:35], v[212:215], v[172:175], v[32:35]
	global_load_dwordx4 v[138:141], v115, s[98:99] offset:384
	v_mfma_f32_16x16x32_bf16 v[28:31], v[200:203], v[176:179], v[28:31]
	global_load_dwordx4 v[120:123], v97, s[100:101] offset:384
	v_mfma_f32_16x16x32_bf16 v[24:27], v[204:207], v[176:179], v[24:27]
	global_load_dwordx4 v[142:145], v107, s[98:99] offset:384
	v_mfma_f32_16x16x32_bf16 v[20:23], v[208:211], v[176:179], v[20:23]
	global_load_dwordx4 v[124:127], v105, s[100:101] offset:384
	v_mfma_f32_16x16x32_bf16 v[16:19], v[212:215], v[176:179], v[16:19]
	global_load_dwordx4 v[150:153], v113, s[98:99] offset:384
	v_mfma_f32_16x16x32_bf16 v[12:15], v[200:203], v[180:183], v[12:15]
	v_mfma_f32_16x16x32_bf16 v[8:11], v[204:207], v[180:183], v[8:11]
	v_mfma_f32_16x16x32_bf16 v[4:7], v[208:211], v[180:183], v[4:7]
	v_mfma_f32_16x16x32_bf16 v[0:3], v[212:215], v[180:183], v[0:3]
	s_setprio 0
	s_barrier
	ds_read_b128 v[184:187], v132 offset:49152
	ds_read_b128 v[168:171], v133 offset:32768
	ds_read_b128 v[188:191], v132 offset:51200
	ds_read_b128 v[192:195], v132 offset:53248
	ds_read_b128 v[196:199], v132 offset:55296
	ds_read_b128 v[172:175], v133 offset:34816
	ds_read_b128 v[176:179], v133 offset:36864
	ds_read_b128 v[180:183], v133 offset:38912
	ds_read_b128 v[200:203], v130 offset:49152
	ds_read_b128 v[204:207], v130 offset:51200
	ds_read_b128 v[208:211], v130 offset:53248
	ds_read_b128 v[212:215], v130 offset:55296
	s_setprio 1
	s_waitcnt lgkmcnt(7)
	v_mfma_f32_16x16x32_bf16 v[92:95], v[184:187], v[168:171], v[92:95]
	v_mfma_f32_16x16x32_bf16 v[88:91], v[188:191], v[168:171], v[88:91]
	v_mfma_f32_16x16x32_bf16 v[84:87], v[192:195], v[168:171], v[84:87]
	v_mfma_f32_16x16x32_bf16 v[146:149], v[196:199], v[168:171], v[146:149]
	ds_read_b128 v[168:171], v131 offset:32768
	s_waitcnt lgkmcnt(5)
	v_mfma_f32_16x16x32_bf16 v[44:47], v[184:187], v[172:175], v[44:47]
	s_waitcnt vmcnt(8)
	ds_write_b128 v166, v[48:51]
	v_mfma_f32_16x16x32_bf16 v[40:43], v[188:191], v[172:175], v[40:43]
	ds_write_b128 v166, v[64:67] offset:16384
	v_mfma_f32_16x16x32_bf16 v[36:39], v[192:195], v[172:175], v[36:39]
	ds_write_b128 v166, v[52:55] offset:4096
	v_mfma_f32_16x16x32_bf16 v[32:35], v[196:199], v[172:175], v[32:35]
	ds_read_b128 v[172:175], v131 offset:34816
	v_mfma_f32_16x16x32_bf16 v[28:31], v[184:187], v[176:179], v[28:31]
	ds_write_b128 v166, v[68:71] offset:20480
	v_mfma_f32_16x16x32_bf16 v[24:27], v[188:191], v[176:179], v[24:27]
	ds_write_b128 v166, v[56:59] offset:8192
	v_mfma_f32_16x16x32_bf16 v[20:23], v[192:195], v[176:179], v[20:23]
	ds_write_b128 v166, v[72:75] offset:24576
	v_mfma_f32_16x16x32_bf16 v[16:19], v[196:199], v[176:179], v[16:19]
	ds_read_b128 v[176:179], v131 offset:36864
	v_mfma_f32_16x16x32_bf16 v[12:15], v[184:187], v[180:183], v[12:15]
	ds_write_b128 v166, v[60:63] offset:12288
	v_mfma_f32_16x16x32_bf16 v[8:11], v[188:191], v[180:183], v[8:11]
	ds_write_b128 v166, v[76:79] offset:28672
	v_mfma_f32_16x16x32_bf16 v[4:7], v[192:195], v[180:183], v[4:7]
	v_mfma_f32_16x16x32_bf16 v[0:3], v[196:199], v[180:183], v[0:3]
	s_waitcnt lgkmcnt(8)
	ds_read_b128 v[180:183], v131 offset:38912
	v_mfma_f32_16x16x32_bf16 v[92:95], v[200:203], v[168:171], v[92:95]
	v_mfma_f32_16x16x32_bf16 v[88:91], v[204:207], v[168:171], v[88:91]
	v_mfma_f32_16x16x32_bf16 v[84:87], v[208:211], v[168:171], v[84:87]
	v_mfma_f32_16x16x32_bf16 v[146:149], v[212:215], v[168:171], v[146:149]
	s_waitcnt lgkmcnt(0)
	v_mfma_f32_16x16x32_bf16 v[44:47], v[200:203], v[172:175], v[44:47]
	global_load_dwordx4 v[48:51], v102, s[100:101] offset:512
	v_mfma_f32_16x16x32_bf16 v[40:43], v[204:207], v[172:175], v[40:43]
	global_load_dwordx4 v[64:67], v114, s[98:99] offset:512
	v_mfma_f32_16x16x32_bf16 v[36:39], v[208:211], v[172:175], v[36:39]
	global_load_dwordx4 v[52:55], v103, s[100:101] offset:512
	v_mfma_f32_16x16x32_bf16 v[32:35], v[212:215], v[172:175], v[32:35]
	global_load_dwordx4 v[68:71], v115, s[98:99] offset:512
	v_mfma_f32_16x16x32_bf16 v[28:31], v[200:203], v[176:179], v[28:31]
	global_load_dwordx4 v[56:59], v97, s[100:101] offset:512
	v_mfma_f32_16x16x32_bf16 v[24:27], v[204:207], v[176:179], v[24:27]
	global_load_dwordx4 v[72:75], v107, s[98:99] offset:512
	v_mfma_f32_16x16x32_bf16 v[20:23], v[208:211], v[176:179], v[20:23]
	global_load_dwordx4 v[60:63], v105, s[100:101] offset:512
	v_mfma_f32_16x16x32_bf16 v[16:19], v[212:215], v[176:179], v[16:19]
	global_load_dwordx4 v[76:79], v113, s[98:99] offset:512
	v_mfma_f32_16x16x32_bf16 v[12:15], v[200:203], v[180:183], v[12:15]
	v_mfma_f32_16x16x32_bf16 v[8:11], v[204:207], v[180:183], v[8:11]
	v_mfma_f32_16x16x32_bf16 v[4:7], v[208:211], v[180:183], v[4:7]
	v_mfma_f32_16x16x32_bf16 v[0:3], v[212:215], v[180:183], v[0:3]
	s_setprio 0
	s_barrier
	s_add_u32 s100, s100, 0x100
	s_addc_u32 s101, s101, 0
	s_add_u32 s98, s98, 0x100
	s_addc_u32 s99, s99, 0
	s_sub_u32 s84, s84, 1
	s_cmp_lg_u32 s84, 0
	s_cbranch_scc1 .Lgm_p8_loop
	ds_read_b128 v[184:187], v132 offset:16384
	ds_read_b128 v[168:171], v133
	ds_read_b128 v[188:191], v132 offset:18432
	ds_read_b128 v[192:195], v132 offset:20480
	ds_read_b128 v[196:199], v132 offset:22528
	ds_read_b128 v[172:175], v133 offset:2048
	ds_read_b128 v[176:179], v133 offset:4096
	ds_read_b128 v[180:183], v133 offset:6144
	ds_read_b128 v[200:203], v130 offset:16384
	ds_read_b128 v[204:207], v130 offset:18432
	ds_read_b128 v[208:211], v130 offset:20480
	ds_read_b128 v[212:215], v130 offset:22528
	s_setprio 1
	s_waitcnt lgkmcnt(7)
	v_mfma_f32_16x16x32_bf16 v[92:95], v[184:187], v[168:171], v[92:95]
	v_mfma_f32_16x16x32_bf16 v[88:91], v[188:191], v[168:171], v[88:91]
	v_mfma_f32_16x16x32_bf16 v[84:87], v[192:195], v[168:171], v[84:87]
	v_mfma_f32_16x16x32_bf16 v[146:149], v[196:199], v[168:171], v[146:149]
	ds_read_b128 v[168:171], v131
	s_waitcnt lgkmcnt(5)
	v_mfma_f32_16x16x32_bf16 v[44:47], v[184:187], v[172:175], v[44:47]
	s_waitcnt vmcnt(8)
	ds_write_b128 v166, v[80:83] offset:32768
	v_mfma_f32_16x16x32_bf16 v[40:43], v[188:191], v[172:175], v[40:43]
	ds_write_b128 v166, v[134:137] offset:49152
	v_mfma_f32_16x16x32_bf16 v[36:39], v[192:195], v[172:175], v[36:39]
	ds_write_b128 v166, v[116:119] offset:36864
	v_mfma_f32_16x16x32_bf16 v[32:35], v[196:199], v[172:175], v[32:35]
	ds_read_b128 v[172:175], v131 offset:2048
	v_mfma_f32_16x16x32_bf16 v[28:31], v[184:187], v[176:179], v[28:31]
	ds_write_b128 v166, v[138:141] offset:53248
	v_mfma_f32_16x16x32_bf16 v[24:27], v[188:191], v[176:179], v[24:27]
	ds_write_b128 v166, v[120:123] offset:40960
	v_mfma_f32_16x16x32_bf16 v[20:23], v[192:195], v[176:179], v[20:23]
	ds_write_b128 v166, v[142:145] offset:57344
	v_mfma_f32_16x16x32_bf16 v[16:19], v[196:199], v[176:179], v[16:19]
	ds_read_b128 v[176:179], v131 offset:4096
	v_mfma_f32_16x16x32_bf16 v[12:15], v[184:187], v[180:183], v[12:15]
	ds_write_b128 v166, v[124:127] offset:45056
	v_mfma_f32_16x16x32_bf16 v[8:11], v[188:191], v[180:183], v[8:11]
	ds_write_b128 v166, v[150:153] offset:61440
	v_mfma_f32_16x16x32_bf16 v[4:7], v[192:195], v[180:183], v[4:7]
	v_mfma_f32_16x16x32_bf16 v[0:3], v[196:199], v[180:183], v[0:3]
	s_waitcnt lgkmcnt(8)
	ds_read_b128 v[180:183], v131 offset:6144
	v_mfma_f32_16x16x32_bf16 v[92:95], v[200:203], v[168:171], v[92:95]
	v_mfma_f32_16x16x32_bf16 v[88:91], v[204:207], v[168:171], v[88:91]
	v_mfma_f32_16x16x32_bf16 v[84:87], v[208:211], v[168:171], v[84:87]
	v_mfma_f32_16x16x32_bf16 v[146:149], v[212:215], v[168:171], v[146:149]
	s_waitcnt lgkmcnt(0)
	v_mfma_f32_16x16x32_bf16 v[44:47], v[200:203], v[172:175], v[44:47]
	global_load_dwordx4 v[80:83], v102, s[100:101] offset:384
	v_mfma_f32_16x16x32_bf16 v[40:43], v[204:207], v[172:175], v[40:43]
	global_load_dwordx4 v[134:137], v114, s[98:99] offset:384
	v_mfma_f32_16x16x32_bf16 v[36:39], v[208:211], v[172:175], v[36:39]
	global_load_dwordx4 v[116:119], v103, s[100:101] offset:384
	v_mfma_f32_16x16x32_bf16 v[32:35], v[212:215], v[172:175], v[32:35]
	global_load_dwordx4 v[138:141], v115, s[98:99] offset:384
	v_mfma_f32_16x16x32_bf16 v[28:31], v[200:203], v[176:179], v[28:31]
	global_load_dwordx4 v[120:123], v97, s[100:101] offset:384
	v_mfma_f32_16x16x32_bf16 v[24:27], v[204:207], v[176:179], v[24:27]
	global_load_dwordx4 v[142:145], v107, s[98:99] offset:384
	v_mfma_f32_16x16x32_bf16 v[20:23], v[208:211], v[176:179], v[20:23]
	global_load_dwordx4 v[124:127], v105, s[100:101] offset:384
	v_mfma_f32_16x16x32_bf16 v[16:19], v[212:215], v[176:179], v[16:19]
	global_load_dwordx4 v[150:153], v113, s[98:99] offset:384
	v_mfma_f32_16x16x32_bf16 v[12:15], v[200:203], v[180:183], v[12:15]
	v_mfma_f32_16x16x32_bf16 v[8:11], v[204:207], v[180:183], v[8:11]
	v_mfma_f32_16x16x32_bf16 v[4:7], v[208:211], v[180:183], v[4:7]
	v_mfma_f32_16x16x32_bf16 v[0:3], v[212:215], v[180:183], v[0:3]
	s_setprio 0
	s_barrier
	ds_read_b128 v[184:187], v132 offset:49152
	ds_read_b128 v[168:171], v133 offset:32768
	ds_read_b128 v[188:191], v132 offset:51200
	ds_read_b128 v[192:195], v132 offset:53248
	ds_read_b128 v[196:199], v132 offset:55296
	ds_read_b128 v[172:175], v133 offset:34816
	ds_read_b128 v[176:179], v133 offset:36864
	ds_read_b128 v[180:183], v133 offset:38912
	ds_read_b128 v[200:203], v130 offset:49152
	ds_read_b128 v[204:207], v130 offset:51200
	ds_read_b128 v[208:211], v130 offset:53248
	ds_read_b128 v[212:215], v130 offset:55296
	s_setprio 1
	s_waitcnt lgkmcnt(7)
	v_mfma_f32_16x16x32_bf16 v[92:95], v[184:187], v[168:171], v[92:95]
	v_mfma_f32_16x16x32_bf16 v[88:91], v[188:191], v[168:171], v[88:91]
	v_mfma_f32_16x16x32_bf16 v[84:87], v[192:195], v[168:171], v[84:87]
	v_mfma_f32_16x16x32_bf16 v[146:149], v[196:199], v[168:171], v[146:149]
	ds_read_b128 v[168:171], v131 offset:32768
	s_waitcnt lgkmcnt(5)
	v_mfma_f32_16x16x32_bf16 v[44:47], v[184:187], v[172:175], v[44:47]
	s_waitcnt vmcnt(8)
	ds_write_b128 v166, v[48:51]
	v_mfma_f32_16x16x32_bf16 v[40:43], v[188:191], v[172:175], v[40:43]
	ds_write_b128 v166, v[64:67] offset:16384
	v_mfma_f32_16x16x32_bf16 v[36:39], v[192:195], v[172:175], v[36:39]
	ds_write_b128 v166, v[52:55] offset:4096
	v_mfma_f32_16x16x32_bf16 v[32:35], v[196:199], v[172:175], v[32:35]
	ds_read_b128 v[172:175], v131 offset:34816
	v_mfma_f32_16x16x32_bf16 v[28:31], v[184:187], v[176:179], v[28:31]
	ds_write_b128 v166, v[68:71] offset:20480
	v_mfma_f32_16x16x32_bf16 v[24:27], v[188:191], v[176:179], v[24:27]
	ds_write_b128 v166, v[56:59] offset:8192
	v_mfma_f32_16x16x32_bf16 v[20:23], v[192:195], v[176:179], v[20:23]
	ds_write_b128 v166, v[72:75] offset:24576
	v_mfma_f32_16x16x32_bf16 v[16:19], v[196:199], v[176:179], v[16:19]
	ds_read_b128 v[176:179], v131 offset:36864
	v_mfma_f32_16x16x32_bf16 v[12:15], v[184:187], v[180:183], v[12:15]
	ds_write_b128 v166, v[60:63] offset:12288
	v_mfma_f32_16x16x32_bf16 v[8:11], v[188:191], v[180:183], v[8:11]
	ds_write_b128 v166, v[76:79] offset:28672
	v_mfma_f32_16x16x32_bf16 v[4:7], v[192:195], v[180:183], v[4:7]
	v_mfma_f32_16x16x32_bf16 v[0:3], v[196:199], v[180:183], v[0:3]
	s_waitcnt lgkmcnt(8)
	ds_read_b128 v[180:183], v131 offset:38912
	v_mfma_f32_16x16x32_bf16 v[92:95], v[200:203], v[168:171], v[92:95]
	v_mfma_f32_16x16x32_bf16 v[88:91], v[204:207], v[168:171], v[88:91]
	v_mfma_f32_16x16x32_bf16 v[84:87], v[208:211], v[168:171], v[84:87]
	v_mfma_f32_16x16x32_bf16 v[146:149], v[212:215], v[168:171], v[146:149]
	s_waitcnt lgkmcnt(0)
	v_mfma_f32_16x16x32_bf16 v[44:47], v[200:203], v[172:175], v[44:47]
	v_mfma_f32_16x16x32_bf16 v[40:43], v[204:207], v[172:175], v[40:43]
	v_mfma_f32_16x16x32_bf16 v[36:39], v[208:211], v[172:175], v[36:39]
	v_mfma_f32_16x16x32_bf16 v[32:35], v[212:215], v[172:175], v[32:35]
	v_mfma_f32_16x16x32_bf16 v[28:31], v[200:203], v[176:179], v[28:31]
	v_mfma_f32_16x16x32_bf16 v[24:27], v[204:207], v[176:179], v[24:27]
	v_mfma_f32_16x16x32_bf16 v[20:23], v[208:211], v[176:179], v[20:23]
	v_mfma_f32_16x16x32_bf16 v[16:19], v[212:215], v[176:179], v[16:19]
	v_mfma_f32_16x16x32_bf16 v[12:15], v[200:203], v[180:183], v[12:15]
	v_mfma_f32_16x16x32_bf16 v[8:11], v[204:207], v[180:183], v[8:11]
	v_mfma_f32_16x16x32_bf16 v[4:7], v[208:211], v[180:183], v[4:7]
	v_mfma_f32_16x16x32_bf16 v[0:3], v[212:215], v[180:183], v[0:3]
	s_setprio 0
	s_barrier
	ds_read_b128 v[184:187], v132 offset:16384
	ds_read_b128 v[168:171], v133
	ds_read_b128 v[188:191], v132 offset:18432
	ds_read_b128 v[192:195], v132 offset:20480
	ds_read_b128 v[196:199], v132 offset:22528
	ds_read_b128 v[172:175], v133 offset:2048
	ds_read_b128 v[176:179], v133 offset:4096
	ds_read_b128 v[180:183], v133 offset:6144
	ds_read_b128 v[200:203], v130 offset:16384
	ds_read_b128 v[204:207], v130 offset:18432
	ds_read_b128 v[208:211], v130 offset:20480
	ds_read_b128 v[212:215], v130 offset:22528
	s_setprio 1
	s_waitcnt lgkmcnt(7)
	v_mfma_f32_16x16x32_bf16 v[92:95], v[184:187], v[168:171], v[92:95]
	v_mfma_f32_16x16x32_bf16 v[88:91], v[188:191], v[168:171], v[88:91]
	v_mfma_f32_16x16x32_bf16 v[84:87], v[192:195], v[168:171], v[84:87]
	v_mfma_f32_16x16x32_bf16 v[146:149], v[196:199], v[168:171], v[146:149]
	ds_read_b128 v[168:171], v131
	s_waitcnt lgkmcnt(5)
	v_mfma_f32_16x16x32_bf16 v[44:47], v[184:187], v[172:175], v[44:47]
	s_waitcnt vmcnt(0)
	ds_write_b128 v166, v[80:83] offset:32768
	v_mfma_f32_16x16x32_bf16 v[40:43], v[188:191], v[172:175], v[40:43]
	ds_write_b128 v166, v[134:137] offset:49152
	v_mfma_f32_16x16x32_bf16 v[36:39], v[192:195], v[172:175], v[36:39]
	ds_write_b128 v166, v[116:119] offset:36864
	v_mfma_f32_16x16x32_bf16 v[32:35], v[196:199], v[172:175], v[32:35]
	ds_read_b128 v[172:175], v131 offset:2048
	v_mfma_f32_16x16x32_bf16 v[28:31], v[184:187], v[176:179], v[28:31]
	ds_write_b128 v166, v[138:141] offset:53248
	v_mfma_f32_16x16x32_bf16 v[24:27], v[188:191], v[176:179], v[24:27]
	ds_write_b128 v166, v[120:123] offset:40960
	v_mfma_f32_16x16x32_bf16 v[20:23], v[192:195], v[176:179], v[20:23]
	ds_write_b128 v166, v[142:145] offset:57344
	v_mfma_f32_16x16x32_bf16 v[16:19], v[196:199], v[176:179], v[16:19]
	ds_read_b128 v[176:179], v131 offset:4096
	v_mfma_f32_16x16x32_bf16 v[12:15], v[184:187], v[180:183], v[12:15]
	ds_write_b128 v166, v[124:127] offset:45056
	v_mfma_f32_16x16x32_bf16 v[8:11], v[188:191], v[180:183], v[8:11]
	ds_write_b128 v166, v[150:153] offset:61440
	v_mfma_f32_16x16x32_bf16 v[4:7], v[192:195], v[180:183], v[4:7]
	v_mfma_f32_16x16x32_bf16 v[0:3], v[196:199], v[180:183], v[0:3]
	s_waitcnt lgkmcnt(8)
	ds_read_b128 v[180:183], v131 offset:6144
	v_mfma_f32_16x16x32_bf16 v[92:95], v[200:203], v[168:171], v[92:95]
	v_mfma_f32_16x16x32_bf16 v[88:91], v[204:207], v[168:171], v[88:91]
	v_mfma_f32_16x16x32_bf16 v[84:87], v[208:211], v[168:171], v[84:87]
	v_mfma_f32_16x16x32_bf16 v[146:149], v[212:215], v[168:171], v[146:149]
	s_waitcnt lgkmcnt(0)
	v_mfma_f32_16x16x32_bf16 v[44:47], v[200:203], v[172:175], v[44:47]
	v_mfma_f32_16x16x32_bf16 v[40:43], v[204:207], v[172:175], v[40:43]
	v_mfma_f32_16x16x32_bf16 v[36:39], v[208:211], v[172:175], v[36:39]
	v_mfma_f32_16x16x32_bf16 v[32:35], v[212:215], v[172:175], v[32:35]
	v_mfma_f32_16x16x32_bf16 v[28:31], v[200:203], v[176:179], v[28:31]
	v_mfma_f32_16x16x32_bf16 v[24:27], v[204:207], v[176:179], v[24:27]
	v_mfma_f32_16x16x32_bf16 v[20:23], v[208:211], v[176:179], v[20:23]
	v_mfma_f32_16x16x32_bf16 v[16:19], v[212:215], v[176:179], v[16:19]
	v_mfma_f32_16x16x32_bf16 v[12:15], v[200:203], v[180:183], v[12:15]
	v_mfma_f32_16x16x32_bf16 v[8:11], v[204:207], v[180:183], v[8:11]
	v_mfma_f32_16x16x32_bf16 v[4:7], v[208:211], v[180:183], v[4:7]
	v_mfma_f32_16x16x32_bf16 v[0:3], v[212:215], v[180:183], v[0:3]
	s_setprio 0
	s_barrier
	ds_read_b128 v[184:187], v132 offset:49152
	ds_read_b128 v[168:171], v133 offset:32768
	ds_read_b128 v[188:191], v132 offset:51200
	ds_read_b128 v[192:195], v132 offset:53248
	ds_read_b128 v[196:199], v132 offset:55296
	ds_read_b128 v[172:175], v133 offset:34816
	ds_read_b128 v[176:179], v133 offset:36864
	ds_read_b128 v[180:183], v133 offset:38912
	ds_read_b128 v[200:203], v130 offset:49152
	ds_read_b128 v[204:207], v130 offset:51200
	ds_read_b128 v[208:211], v130 offset:53248
	ds_read_b128 v[212:215], v130 offset:55296
	s_setprio 1
	s_waitcnt lgkmcnt(7)
	v_mfma_f32_16x16x32_bf16 v[92:95], v[184:187], v[168:171], v[92:95]
	v_mfma_f32_16x16x32_bf16 v[88:91], v[188:191], v[168:171], v[88:91]
	v_mfma_f32_16x16x32_bf16 v[84:87], v[192:195], v[168:171], v[84:87]
	v_mfma_f32_16x16x32_bf16 v[146:149], v[196:199], v[168:171], v[146:149]
	ds_read_b128 v[168:171], v131 offset:32768
	s_waitcnt lgkmcnt(5)
	v_mfma_f32_16x16x32_bf16 v[44:47], v[184:187], v[172:175], v[44:47]
	v_mfma_f32_16x16x32_bf16 v[40:43], v[188:191], v[172:175], v[40:43]
	v_mfma_f32_16x16x32_bf16 v[36:39], v[192:195], v[172:175], v[36:39]
	v_mfma_f32_16x16x32_bf16 v[32:35], v[196:199], v[172:175], v[32:35]
	ds_read_b128 v[172:175], v131 offset:34816
	v_mfma_f32_16x16x32_bf16 v[28:31], v[184:187], v[176:179], v[28:31]
	v_mfma_f32_16x16x32_bf16 v[24:27], v[188:191], v[176:179], v[24:27]
	v_mfma_f32_16x16x32_bf16 v[20:23], v[192:195], v[176:179], v[20:23]
	v_mfma_f32_16x16x32_bf16 v[16:19], v[196:199], v[176:179], v[16:19]
	ds_read_b128 v[176:179], v131 offset:36864
	v_mfma_f32_16x16x32_bf16 v[12:15], v[184:187], v[180:183], v[12:15]
	v_mfma_f32_16x16x32_bf16 v[8:11], v[188:191], v[180:183], v[8:11]
	v_mfma_f32_16x16x32_bf16 v[4:7], v[192:195], v[180:183], v[4:7]
	v_mfma_f32_16x16x32_bf16 v[0:3], v[196:199], v[180:183], v[0:3]
	ds_read_b128 v[180:183], v131 offset:38912
	s_waitcnt lgkmcnt(3)
	v_mfma_f32_16x16x32_bf16 v[92:95], v[200:203], v[168:171], v[92:95]
	v_mfma_f32_16x16x32_bf16 v[88:91], v[204:207], v[168:171], v[88:91]
	v_mfma_f32_16x16x32_bf16 v[84:87], v[208:211], v[168:171], v[84:87]
	v_mfma_f32_16x16x32_bf16 v[146:149], v[212:215], v[168:171], v[146:149]
	s_waitcnt lgkmcnt(0)
	v_mfma_f32_16x16x32_bf16 v[44:47], v[200:203], v[172:175], v[44:47]
	v_mfma_f32_16x16x32_bf16 v[40:43], v[204:207], v[172:175], v[40:43]
	v_mfma_f32_16x16x32_bf16 v[36:39], v[208:211], v[172:175], v[36:39]
	v_mfma_f32_16x16x32_bf16 v[32:35], v[212:215], v[172:175], v[32:35]
	v_mfma_f32_16x16x32_bf16 v[28:31], v[200:203], v[176:179], v[28:31]
	v_mfma_f32_16x16x32_bf16 v[24:27], v[204:207], v[176:179], v[24:27]
	v_mfma_f32_16x16x32_bf16 v[20:23], v[208:211], v[176:179], v[20:23]
	v_mfma_f32_16x16x32_bf16 v[16:19], v[212:215], v[176:179], v[16:19]
	v_mfma_f32_16x16x32_bf16 v[12:15], v[200:203], v[180:183], v[12:15]
	v_mfma_f32_16x16x32_bf16 v[8:11], v[204:207], v[180:183], v[8:11]
	v_mfma_f32_16x16x32_bf16 v[4:7], v[208:211], v[180:183], v[4:7]
	v_mfma_f32_16x16x32_bf16 v[0:3], v[212:215], v[180:183], v[0:3]
	s_setprio 0
	s_nop 7
	v_add_u32_e32 v102, s5, v167
	v_ashrrev_i32_e32 v103, 31, v102
	v_lshlrev_b64 v[48:49], 12, v[102:103]
	v_or_b32_e32 v64, 16, v102
	v_or_b32_e32 v80, 32, v102
	v_or_b32_e32 v102, 48, v102
	v_ashrrev_i32_e32 v65, 31, v64
	v_ashrrev_i32_e32 v81, 31, v80
	v_ashrrev_i32_e32 v103, 31, v102
	s_ashr_i32 s5, s4, 31
	v_lshlrev_b64 v[64:65], 12, v[64:65]
	v_lshlrev_b64 v[80:81], 12, v[80:81]
	v_lshlrev_b64 v[102:103], 12, v[102:103]
	v_lshl_add_u64 v[48:49], s[88:89], 0, v[48:49]
	s_lshl_b64 s[4:5], s[4:5], 2
	v_lshl_add_u64 v[64:65], s[88:89], 0, v[64:65]
	v_lshl_add_u64 v[80:81], s[88:89], 0, v[80:81]
	v_lshl_add_u64 v[102:103], s[88:89], 0, v[102:103]
	v_lshl_add_u64 v[48:49], v[48:49], 0, s[4:5]
	v_lshl_add_u64 v[64:65], v[64:65], 0, s[4:5]
	v_lshl_add_u64 v[80:81], v[80:81], 0, s[4:5]
	v_lshl_add_u64 v[102:103], v[102:103], 0, s[4:5]
	v_lshl_add_u64 v[48:49], v[48:49], 0, v[110:111]
	v_lshlrev_b32_e32 v126, 2, v108
	v_mov_b32_e32 v127, v111
	v_lshl_add_u64 v[64:65], v[64:65], 0, v[110:111]
	v_lshl_add_u64 v[80:81], v[80:81], 0, v[110:111]
	v_lshl_add_u64 v[102:103], v[102:103], 0, v[110:111]
	v_lshl_add_u64 v[150:151], v[48:49], 0, v[126:127]
	v_lshl_add_u64 v[152:153], v[64:65], 0, v[126:127]
	v_lshl_add_u64 v[164:165], v[80:81], 0, v[126:127]
	v_lshl_add_u64 v[102:103], v[102:103], 0, v[126:127]
	global_load_dwordx4 v[48:51], v[150:151], off
	global_load_dwordx4 v[52:55], v[150:151], off offset:64
	global_load_dwordx4 v[56:59], v[150:151], off offset:128
	global_load_dwordx4 v[60:63], v[150:151], off offset:192
	global_load_dwordx4 v[64:67], v[152:153], off
	global_load_dwordx4 v[68:71], v[152:153], off offset:64
	global_load_dwordx4 v[72:75], v[152:153], off offset:128
	global_load_dwordx4 v[76:79], v[152:153], off offset:192
	global_load_dwordx4 v[80:83], v[164:165], off
	global_load_dwordx4 v[114:117], v[164:165], off offset:64
	global_load_dwordx4 v[118:121], v[164:165], off offset:128
	global_load_dwordx4 v[122:125], v[164:165], off offset:192
	global_load_dwordx4 v[126:129], v[102:103], off
	global_load_dwordx4 v[134:137], v[102:103], off offset:64
	global_load_dwordx4 v[138:141], v[102:103], off offset:128
	global_load_dwordx4 v[142:145], v[102:103], off offset:192
	s_mov_b32 s8, 0
	s_waitcnt vmcnt(15)
	v_pk_add_f32 v[48:49], v[92:93], v[48:49]
	v_pk_add_f32 v[50:51], v[94:95], v[50:51]
	s_waitcnt vmcnt(11)
	v_pk_add_f32 v[44:45], v[44:45], v[64:65]
	v_pk_add_f32 v[46:47], v[46:47], v[66:67]
	v_pk_add_f32 v[52:53], v[88:89], v[52:53]
	s_waitcnt vmcnt(1)
	v_pk_add_f32 v[4:5], v[4:5], v[138:139]
	v_pk_add_f32 v[6:7], v[6:7], v[140:141]
	s_waitcnt vmcnt(0)
	v_pk_add_f32 v[0:1], v[0:1], v[142:143]
	v_pk_add_f32 v[2:3], v[2:3], v[144:145]
	v_pk_add_f32 v[54:55], v[90:91], v[54:55]
	v_pk_add_f32 v[56:57], v[84:85], v[56:57]
	v_pk_add_f32 v[58:59], v[86:87], v[58:59]
	v_pk_add_f32 v[60:61], v[146:147], v[60:61]
	v_pk_add_f32 v[62:63], v[148:149], v[62:63]
	global_store_dwordx4 v[150:151], v[48:51], off
	global_store_dwordx4 v[150:151], v[52:55], off offset:64
	global_store_dwordx4 v[150:151], v[56:59], off offset:128
	global_store_dwordx4 v[150:151], v[60:63], off offset:192
	v_pk_add_f32 v[40:41], v[40:41], v[68:69]
	v_pk_add_f32 v[42:43], v[42:43], v[70:71]
	v_pk_add_f32 v[36:37], v[36:37], v[72:73]
	v_pk_add_f32 v[38:39], v[38:39], v[74:75]
	v_pk_add_f32 v[32:33], v[32:33], v[76:77]
	v_pk_add_f32 v[34:35], v[34:35], v[78:79]
	v_pk_add_f32 v[28:29], v[28:29], v[80:81]
	v_pk_add_f32 v[30:31], v[30:31], v[82:83]
	v_pk_add_f32 v[24:25], v[24:25], v[114:115]
	v_pk_add_f32 v[26:27], v[26:27], v[116:117]
	v_pk_add_f32 v[20:21], v[20:21], v[118:119]
	v_pk_add_f32 v[22:23], v[22:23], v[120:121]
	v_pk_add_f32 v[16:17], v[16:17], v[122:123]
	v_pk_add_f32 v[18:19], v[18:19], v[124:125]
	v_pk_add_f32 v[12:13], v[12:13], v[126:127]
	v_pk_add_f32 v[14:15], v[14:15], v[128:129]
	v_pk_add_f32 v[8:9], v[8:9], v[134:135]
	v_pk_add_f32 v[10:11], v[10:11], v[136:137]
	global_store_dwordx4 v[152:153], v[44:47], off
	global_store_dwordx4 v[152:153], v[40:43], off offset:64
	global_store_dwordx4 v[152:153], v[36:39], off offset:128
	global_store_dwordx4 v[152:153], v[32:35], off offset:192
	global_store_dwordx4 v[164:165], v[28:31], off
	global_store_dwordx4 v[164:165], v[24:27], off offset:64
	global_store_dwordx4 v[164:165], v[20:23], off offset:128
	global_store_dwordx4 v[164:165], v[16:19], off offset:192
	global_store_dwordx4 v[102:103], v[12:15], off
	global_store_dwordx4 v[102:103], v[8:11], off offset:64
	global_store_dwordx4 v[102:103], v[4:7], off offset:128
	global_store_dwordx4 v[102:103], v[0:3], off offset:192
	s_mov_b64 s[4:5], -1
	s_cmp_gt_i32 s8, 3
	s_mov_b64 s[6:7], -1
	s_cbranch_scc1 .LBB0_919
